# skip L2 writeback at XCD-local barriers B4 B5 B8 B9 (runtime-checked WG->XCD map), sample-row stores write-through
# baseline (speedup 1.0000x reference)
; #define LAS __attribute__((address_space(3)))
; __device__ __forceinline__ unsigned xb_add(unsigned* p, unsigned v) { return __hip_atomic_fetch_add(p, v, __ATOMIC_RELAXED, __HIP_MEMORY_SCOPE_AGENT); }
; __device__ __forceinline__ unsigned xb_xcc_id() { return (unsigned)__builtin_amdgcn_s_getreg((3 << 11) | 20) & 0xFu; }
; __device__ __forceinline__ XcdBarrier xcd_barrier_post(unsigned* bar, volatile LAS unsigned* st) {
;     XcdBarrier b; b.bar = bar; b.x = xb_xcc_id(); b.st = st;
;     if (threadIdx.x == 0) (void)xb_add(&bar[XB_XCNT(b.x)], 1u);
;     return b;
; }
; __global__ void __launch_bounds__(512, 2) fwd_megakernel(Params p) {
;     ...
;     { volatile LAS unsigned* st0 = (volatile LAS unsigned*)(F.lds + RING_BYTES + 12288); if (F.tid < 4) st0[F.tid] = 0u; }
;     __syncthreads();
;     const XcdBarrier xbar = xcd_barrier_post((unsigned*)ws, (volatile LAS unsigned*)(F.lds + RING_BYTES + 12288));
.LBB0_2:
	s_load_dword s3, s[0:1], 0x148
	s_load_dwordx16 s[44:59], s[0:1], 0x100
	v_and_b32_e32 v202, 0x3ff, v0
	v_cmp_gt_u32_e32 vcc, 4, v202
	s_waitcnt lgkmcnt(0)
	v_writelane_b32 v254, s3, 2
	s_and_saveexec_b64 s[4:5], vcc
	v_lshl_add_u32 v1, v202, 2, 0
	v_add_u32_e32 v1, 0x23000, v1
	v_mov_b32_e32 v2, 0
	ds_write_b32 v1, v2
	s_or_b64 exec, exec, s[4:5]
	s_load_dwordx16 s[4:19], s[0:1], 0xc0
	s_waitcnt lgkmcnt(0)
	s_barrier
	s_getreg_b32 s3, hwreg(HW_REG_XCC_ID, 0, 4)
	v_writelane_b32 v254, s4, 3
	s_and_b32 s3, s3, 15
	s_nop 0
	v_writelane_b32 v254, s5, 4
	v_writelane_b32 v254, s6, 5
	v_writelane_b32 v254, s7, 6
	v_writelane_b32 v254, s8, 7
	v_writelane_b32 v254, s9, 8
	v_writelane_b32 v254, s10, 9
	v_writelane_b32 v254, s11, 10
	v_writelane_b32 v254, s12, 11
	v_writelane_b32 v254, s13, 12
	v_writelane_b32 v254, s14, 13
	v_writelane_b32 v254, s15, 14
	v_writelane_b32 v254, s16, 15
	v_writelane_b32 v254, s17, 16
	v_writelane_b32 v254, s18, 17
	v_writelane_b32 v254, s19, 18
	v_writelane_b32 v254, s3, 19
	v_cmp_eq_u32_e64 s[6:7], 0, v202
	s_mov_b64 s[4:5], exec
	s_nop 0
	v_writelane_b32 v254, s6, 20
	s_nop 1
	v_writelane_b32 v254, s7, 21
	s_and_b64 s[6:7], s[4:5], s[6:7]
	s_mov_b64 exec, s[6:7]
	s_cbranch_execz .LBB0_7
	s_mov_b64 s[6:7], exec
	v_mbcnt_lo_u32_b32 v1, s6, 0
	v_mbcnt_hi_u32_b32 v1, s7, v1
	v_cmp_eq_u32_e32 vcc, 0, v1
	s_and_b64 s[8:9], exec, vcc
	s_mov_b64 exec, s[8:9]
	s_cbranch_execz .LBB0_7
	v_readlane_b32 s3, v254, 19
	s_lshl_b32 s3, s3, 8
	s_bcnt1_i32_b64 s6, s[6:7]
	v_mov_b32_e32 v1, s3
	v_mov_b32_e32 v2, s6
	global_atomic_add v1, v2, s[58:59] offset:1024
	s_lshr_b32 s3, s3, 8
	s_and_b32 s6, s2, 7
	s_cmp_eq_u32 s3, s6
	s_cbranch_scc1 .Lxmap_ok
	v_mov_b32_e32 v3, 0x3700
	v_mov_b32_e32 v4, 1
	global_store_dword v3, v4, s[58:59] sc0 sc1
; #define LAS __attribute__((address_space(3)))
; __device__ __forceinline__ Frame fresh(const Frame& F0) { Frame F = F0; int t = threadIdx.x; asm volatile("" : "+v"(t)); F.tid = t; F.lane = t & 63; F.wave = __builtin_amdgcn_readfirstlane(t >> 6); return F; }
; __device__ __forceinline__ void p0_prologue(const Params& p, const Frame& F0) {
;     const Frame F = fresh(F0);
;     LAS float* scr = (LAS float*)(F.lds + F.wave * 16384);
;     const int gw = F.vcu * 8 + F.wave, NGW = F.G * 8;
;     bf16_t* Win_t = (bf16_t*)(p.ws + WS_WIN); bf16_t* Glu_t = (bf16_t*)(p.ws + WS_GLU); bf16_t* Wout_t = (bf16_t*)(p.ws + WS_WOUT); bf16_t* Wq_t = (bf16_t*)(p.ws + WS_WQ);
;     bf16_t* Wkv_t = (bf16_t*)(p.ws + WS_WKV); bf16_t* Wo_t = (bf16_t*)(p.ws + WS_WO); bf16_t* W1_t = (bf16_t*)(p.ws + WS_W1); bf16_t* W2_t = (bf16_t*)(p.ws + WS_W2);
;     bf16_t* Vt = (bf16_t*)(p.ws + WS_VT);
;     constexpr int I_IN = 16 * 48, I_GLU = 8 * 16, I_SQ = 16 * 32, I_1 = 16 * 128, I_2 = 64 * 32, I_VT = 16 * 4 * 32;
;     constexpr int NITEMS = I_IN + I_GLU + 5 * I_SQ + I_1 + I_2 + I_VT;
;     for (int it = gw; it < NITEMS; it += NGW) {
;         int r = it;
;         if (r < I_IN) { const int kb = r / 48, nb = r % 48; transpose_item(p.in[8], DM, DIN, Win_t, DM, 64 * kb, 32 * nb, win_dest_row(32 * nb), scr, F.lane); continue; } r -= I_IN;
.Lxmap_ok:
.LBB0_7:
	s_or_b64 exec, exec, s[4:5]
	s_load_dwordx16 s[4:19], s[0:1], 0x0
	s_add_u32 s3, s58, 0x2d00000
	v_mov_b32_e32 v34, v202
	s_mov_b32 s62, s20
	s_waitcnt lgkmcnt(0)
	v_writelane_b32 v254, s4, 22
	v_and_b32_e32 v1, 7, v34
	s_nop 0
	v_writelane_b32 v254, s5, 23
	v_writelane_b32 v254, s6, 24
	v_writelane_b32 v254, s7, 25
	v_writelane_b32 v254, s8, 26
	v_writelane_b32 v254, s9, 27
	v_writelane_b32 v254, s10, 28
	v_writelane_b32 v254, s11, 29
	v_writelane_b32 v254, s12, 30
	v_writelane_b32 v254, s13, 31
	v_writelane_b32 v254, s14, 32
	v_writelane_b32 v254, s15, 33
	v_writelane_b32 v254, s16, 34
	v_writelane_b32 v254, s17, 35
	v_writelane_b32 v254, s18, 36
	v_writelane_b32 v254, s19, 37
	s_load_dwordx16 s[4:19], s[0:1], 0x40
	s_waitcnt lgkmcnt(0)
	v_writelane_b32 v254, s4, 38
	s_nop 1
	v_writelane_b32 v254, s5, 39
	v_writelane_b32 v254, s6, 40
	v_writelane_b32 v254, s7, 41
	v_writelane_b32 v254, s8, 42
	v_writelane_b32 v254, s9, 43
	v_writelane_b32 v254, s10, 44
	v_writelane_b32 v254, s11, 45
	v_writelane_b32 v254, s12, 46
	v_writelane_b32 v254, s13, 47
	v_writelane_b32 v254, s14, 48
	v_writelane_b32 v254, s15, 49
	v_writelane_b32 v254, s16, 50
	v_writelane_b32 v254, s17, 51
	v_writelane_b32 v254, s18, 52
	v_writelane_b32 v254, s19, 53
	v_writelane_b32 v254, s3, 54
	s_addc_u32 s3, s59, 0
	v_writelane_b32 v254, s3, 55
	v_readfirstlane_b32 s3, v34
	s_ashr_i32 s3, s3, 6
	s_lshl_b32 s4, s20, 3
	s_add_i32 s26, s3, s4
	s_lshl_b32 s33, s92, 3
	v_writelane_b32 v254, s4, 56
	s_add_u32 s4, s58, 0x500000
	s_addc_u32 s5, s59, 0
	v_writelane_b32 v254, s4, 57
	s_nop 1
	v_writelane_b32 v254, s5, 58
	s_add_u32 s4, s58, 0x700000
	s_addc_u32 s5, s59, 0
	v_writelane_b32 v254, s4, 59
	s_add_u32 s20, s58, 0x900000
	s_addc_u32 s21, s59, 0
	v_writelane_b32 v254, s5, 60
	s_load_dwordx16 s[4:19], s[0:1], 0x80
	s_cmpk_gt_i32 s26, 0x257f
	s_waitcnt lgkmcnt(0)
	v_writelane_b32 v254, s4, 61
	s_nop 1
	v_writelane_b32 v255, s7, 0
	v_writelane_b32 v255, s8, 1
	v_writelane_b32 v255, s9, 2
	v_writelane_b32 v255, s10, 3
	v_writelane_b32 v255, s11, 4
	v_writelane_b32 v255, s12, 5
	v_writelane_b32 v255, s13, 6
	v_writelane_b32 v255, s14, 7
	v_writelane_b32 v255, s15, 8
	v_writelane_b32 v255, s16, 9
	v_writelane_b32 v255, s17, 10
	v_writelane_b32 v255, s18, 11
	v_writelane_b32 v255, s19, 12
	v_writelane_b32 v254, s5, 62
	v_writelane_b32 v255, s20, 13
	v_writelane_b32 v254, s6, 63
	s_nop 0
	v_writelane_b32 v255, s21, 14
	s_cbranch_scc1 .LBB0_156
	s_lshl_b32 s0, s3, 14
	v_bfe_u32 v9, v34, 5, 1
	v_and_b32_e32 v2, 31, v34
	s_add_i32 s0, s0, 0
	v_lshlrev_b32_e32 v4, 2, v2
	v_mul_u32_u24_e32 v3, 0x84, v9
	v_bfe_u32 v10, v34, 3, 3
	v_mov_b32_e32 v7, 0
	v_add3_u32 v11, s0, v4, v3
	v_mul_u32_u24_e32 v3, 0x420, v1
	v_lshlrev_b32_e32 v5, 2, v10
	v_readlane_b32 s4, v254, 61
	v_add3_u32 v13, s0, v3, v5
	v_mov_b32_e32 v5, v7
	v_readlane_b32 s5, v254, 62
	v_readlane_b32 s6, v254, 63
	v_readlane_b32 s7, v255, 0
	v_readlane_b32 s8, v255, 1
	v_readlane_b32 s9, v255, 2
	v_readlane_b32 s10, v255, 3
	v_readlane_b32 s11, v255, 4
	v_readlane_b32 s12, v255, 5
	v_readlane_b32 s13, v255, 6
	v_readlane_b32 s14, v255, 7
	v_readlane_b32 s15, v255, 8
	v_readlane_b32 s16, v255, 9
	v_readlane_b32 s17, v255, 10
	v_readlane_b32 s18, v255, 11
	v_readlane_b32 s19, v255, 12
	v_lshl_add_u64 v[30:31], s[6:7], 0, v[4:5]
	v_readlane_b32 s4, v254, 38
	s_add_u32 s96, s58, 0x3620000
	v_readlane_b32 s5, v254, 39
	v_readlane_b32 s6, v254, 40
	v_readlane_b32 s7, v254, 41
	v_readlane_b32 s8, v254, 42
	v_readlane_b32 s9, v254, 43
	v_readlane_b32 s10, v254, 44
	v_readlane_b32 s11, v254, 45
	v_readlane_b32 s12, v254, 46
	v_readlane_b32 s13, v254, 47
	v_readlane_b32 s14, v254, 48
	v_readlane_b32 s15, v254, 49
	v_readlane_b32 s16, v254, 50
	v_readlane_b32 s17, v254, 51
	v_readlane_b32 s18, v254, 52
	v_readlane_b32 s19, v254, 53
	s_addc_u32 s97, s59, 0
	v_lshl_add_u64 v[32:33], s[4:5], 0, v[4:5]
	s_add_u32 s40, s58, 0x3660000
	v_readlane_b32 s4, v254, 3
	s_addc_u32 s41, s59, 0
	v_readlane_b32 s16, v254, 15
	v_readlane_b32 s17, v254, 16
	v_readlane_b32 s6, v254, 5
	v_readlane_b32 s7, v254, 6
	v_readlane_b32 s8, v254, 7
	s_cmp_lg_u64 s[16:17], 0
	v_lshlrev_b32_e32 v6, 4, v1
	v_readlane_b32 s9, v254, 8
	s_cselect_b64 s[6:7], -1, 0
	s_add_u32 s8, s58, 0x3600000
	v_lshl_add_u64 v[24:25], s[58:59], 0, v[6:7]
	s_mov_b64 s[0:1], 0x1700000
	v_readlane_b32 s10, v254, 9
	s_addc_u32 s9, s59, 0
	v_lshl_add_u64 v[18:19], v[24:25], 0, s[0:1]
	s_mov_b64 s[0:1], 0xf00000
	v_readlane_b32 s11, v254, 10
	s_add_u32 s10, s58, 0x3610000
	v_lshl_add_u64 v[20:21], v[24:25], 0, s[0:1]
	s_mov_b64 s[0:1], 0x400000
	v_readlane_b32 s5, v254, 4
	s_addc_u32 s11, s59, 0
	v_lshl_add_u64 v[22:23], v[24:25], 0, s[0:1]
	s_mov_b64 s[0:1], 0x100000
	s_cmp_lg_u64 s[4:5], 0
	v_lshlrev_b32_e32 v8, 3, v1
	v_lshl_add_u64 v[24:25], v[24:25], 0, s[0:1]
	v_readlane_b32 s12, v254, 11
	v_readlane_b32 s13, v254, 12
	v_readlane_b32 s14, v254, 13
	v_readlane_b32 s15, v254, 14
	v_readlane_b32 s19, v254, 18
	s_cselect_b64 s[16:17], -1, 0
	s_lshl_b32 s0, s26, 6
	v_lshlrev_b32_e32 v36, 2, v2
	v_mbcnt_lo_u32_b32 v2, -1, 0
	v_or_b32_e32 v12, 8, v10
	v_or_b32_e32 v14, 16, v10
	v_or_b32_e32 v16, 24, v10
	v_lshl_add_u64 v[26:27], s[48:49], 0, v[4:5]
	v_lshl_add_u64 v[28:29], s[44:45], 0, v[4:5]
	s_lshl_b32 s27, s26, 5
	s_lshl_b32 s28, s33, 5
	s_add_i32 s29, s0, 0x7ffffc00
	s_lshl_b32 s30, s33, 6
	s_lshl_b32 s31, s26, 1
	s_lshl_b32 s34, s33, 1
	s_lshl_b32 s35, s26, 2
	s_lshl_b32 s36, s33, 2
	s_movk_i32 s14, 0x2000
	s_movk_i32 s15, 0x4000
	v_add_u32_e32 v15, 0x400, v11
	v_add_u32_e32 v17, 0x800, v11
	v_add_u32_e32 v35, 0xc00, v11
	v_add_u32_e32 v48, 0x1000, v11
	v_add_u32_e32 v49, 0x1400, v11
	v_add_u32_e32 v50, 0x1800, v11
	v_add_u32_e32 v51, 0x1c00, v11
	v_lshlrev_b32_e32 v6, 1, v8
	v_mbcnt_hi_u32_b32 v52, -1, v2
	s_movk_i32 s63, 0x6000
	s_mov_b32 s64, 0x8000
	s_mov_b32 s65, 0xa000
	s_mov_b32 s66, 0xc000
	s_mov_b32 s67, 0xe000
	s_mov_b32 s68, 0x10000
	s_mov_b32 s69, 0x12000
	s_mov_b32 s70, 0x14000
	s_mov_b32 s71, 0x16000
	s_mov_b32 s72, 0x18000
	s_mov_b32 s73, 0x1a000
	s_mov_b32 s74, 0x1c000
	s_mov_b32 s75, 0x1e000
	s_mov_b32 s94, 0x20000
	s_mov_b32 s12, 0x26000
	s_mov_b32 s13, 0x28000
	s_mov_b32 s42, 0x2a000
	s_mov_b32 s43, 0x2c000
	s_mov_b32 s44, 0x2e000
	s_mov_b32 s45, 0x30000
	s_mov_b32 s48, 0x32000
	s_mov_b32 s49, 0x34000
	s_mov_b32 s60, 0x36000
	s_mov_b32 s61, 0x38000
	s_mov_b32 s95, 0x3a000
	s_mov_b32 s3, 0x3c000
	s_mov_b32 s37, 0x3e000
	s_movk_i32 s38, 0x1800
	s_mov_b32 s19, 0
	v_cmp_eq_u32_e64 s[0:1], 0, v1
	v_readlane_b32 s18, v254, 17
	s_branch .LBB0_11

; __device__ __forceinline__ unsigned xb_ld(unsigned* p)              { return __hip_atomic_load(p, __ATOMIC_RELAXED, __HIP_MEMORY_SCOPE_AGENT); }
; __device__ __forceinline__ unsigned xb_add(unsigned* p, unsigned v) { return __hip_atomic_fetch_add(p, v, __ATOMIC_RELAXED, __HIP_MEMORY_SCOPE_AGENT); }
; #define XB_SPIN(cond, bar) do { unsigned _sp = 0; while (cond) { __builtin_amdgcn_s_sleep(1); \
;     if ((++_sp & 255u) == 0u) { if (xb_ld(&(bar)[XB_TMO])) break; if (_sp > XB_SPIN_CAP) { atomicAdd(&(bar)[XB_TMO], 1u); break; } } } } while (0)
; __device__ __forceinline__ void xcd_barrier(const XcdBarrier& b) {
;     asm volatile("s_waitcnt vmcnt(0)" ::: "memory");
;     __syncthreads();
;     if (threadIdx.x == 0) {
;         unsigned* bar = b.bar;
;         __builtin_amdgcn_s_waitcnt(0);
;         unsigned nloc = b.st[0], nx = b.st[1];
;         if (nloc == 0u) { xcd_barrier_complete(bar, b.x, nloc, nx); b.st[0] = nloc; b.st[1] = nx; }
;         const unsigned old = xb_add(&bar[XB_XSUB(b.x)], 1u);
;         const unsigned gen = old / nloc;
;         if (old + 1u == (gen + 1u) * nloc) {
;             __builtin_amdgcn_fence(__ATOMIC_RELEASE, "agent");
;             asm volatile("s_waitcnt vmcnt(0)" ::: "memory");
;             const unsigned og = xb_add(&bar[XB_TOP], 1u);
;             const unsigned tg = og / nx;
;             if (og + 1u == (tg + 1u) * nx) xb_add(&bar[XB_TOPGEN], 1u);
;             else XB_SPIN(xb_ld(&bar[XB_TOPGEN]) == tg, bar);
;             __builtin_amdgcn_fence(__ATOMIC_ACQUIRE, "agent");
;             xb_add(&bar[XB_XGEN(b.x)], 1u);
;             asm volatile("s_waitcnt vmcnt(0)" ::: "memory");
;         } else {
;             XB_SPIN(xb_ld(&bar[XB_XGEN(b.x)]) == gen, bar);
.LBB0_468:
	s_mov_b64 s[6:7], exec
	v_readlane_b32 s3, v254, 19
	s_lshl_b32 s3, s3, 8
	v_mbcnt_lo_u32_b32 v1, s6, 0
	s_add_u32 s4, s58, s3
	v_mbcnt_hi_u32_b32 v1, s7, v1
	s_addc_u32 s5, s59, 0
	v_cmp_eq_u32_e32 vcc, 0, v1
	s_and_saveexec_b64 s[8:9], vcc
	s_cbranch_execz .LBB0_470
	s_bcnt1_i32_b64 s3, s[6:7]
	v_mov_b32_e32 v3, 0x1000
	v_mov_b32_e32 v4, s3
	global_atomic_add v3, v3, v4, s[4:5] offset:1024 sc0
	v_mov_b32_e32 v5, 0x3700
	global_load_dword v5, v5, s[58:59] sc0 sc1
.LBB0_470:
	s_or_b64 exec, exec, s[8:9]
	v_cvt_f32_u32_e32 v4, v2
	s_waitcnt vmcnt(0)
	v_readfirstlane_b32 s3, v5
	s_nop 1
	v_writelane_b32 v255, s3, 40
	v_readfirstlane_b32 s3, v3
	v_sub_u32_e32 v3, 0, v2
	v_rcp_iflag_f32_e32 v4, v4
	v_add_u32_e32 v5, s3, v1
	v_mul_f32_e32 v4, 0x4f7ffffe, v4
	v_cvt_u32_f32_e32 v4, v4
	v_mul_lo_u32 v1, v3, v4
	v_mul_hi_u32 v1, v4, v1
	v_add_u32_e32 v1, v4, v1
	v_mul_hi_u32 v1, v5, v1
	v_mul_lo_u32 v3, v1, v2
	v_sub_u32_e32 v3, v5, v3
	v_add_u32_e32 v4, 1, v1
	v_cmp_ge_u32_e32 vcc, v3, v2
	s_nop 1
	v_cndmask_b32_e32 v1, v1, v4, vcc
	v_sub_u32_e32 v4, v3, v2
	v_cndmask_b32_e32 v3, v3, v4, vcc
	v_add_u32_e32 v4, 1, v1
	v_cmp_ge_u32_e32 vcc, v3, v2
	v_add_u32_e32 v3, 1, v5
	s_nop 0
	v_cndmask_b32_e32 v1, v1, v4, vcc
	v_mul_lo_u32 v4, v2, v1
	v_add_u32_e32 v2, v4, v2
	v_cmp_ne_u32_e32 vcc, v3, v2
	s_and_saveexec_b64 s[6:7], vcc
	s_xor_b64 s[6:7], exec, s[6:7]
	s_cbranch_execz .LBB0_484
	s_waitcnt lgkmcnt(0)
	v_mov_b32_e32 v0, 0x2000
	global_load_dword v0, v0, s[4:5] offset:1024 sc1
	s_add_u32 s10, s4, 0x2400
	s_addc_u32 s11, s5, 0
	s_waitcnt vmcnt(0)
	v_cmp_eq_u32_e32 vcc, v0, v1
	s_and_saveexec_b64 s[8:9], vcc
	s_cbranch_execz .LBB0_483
	s_mov_b32 s3, 1
	s_mov_b64 s[12:13], 0
	v_mov_b32_e32 v0, 0
	s_branch .LBB0_474

; #define LAS __attribute__((address_space(3)))
; template <class Epi, bool PAIR>
; __device__ __forceinline__ void small_gemm(LAS unsigned char* lds, const bf16_t* A, int lda, const bf16_t* B, int ldb, int K, int nrg, int nct, size_t row_base, int col_base, const Epi& E, int G, int c) {
;     ...
;     for (int unit = c; unit < nrg * nct; unit += G) {
;         const int rg = unit % nrg, ct = unit / nrg;
;         f32x4 acc[4][4];
; #pragma unroll
;         for (int mi = 0; mi < 4; ++mi)
; #pragma unroll
;             for (int ni = 0; ni < 4; ++ni) acc[mi][ni] = (f32x4){0.f, 0.f, 0.f, 0.f};
;         const bf16_t* ap = A + (size_t)(rg * 64 + fr) * lda + k0 + fq * 8;
;         const bf16_t* bp;
;         if (PAIR) { const int ch0 = 32 * ct; bp = B + (size_t)(DSSM + 256 * (ch0 >> 7) + (ch0 & 127) + fr) * ldb + k0 + fq * 8; }
;         else bp = B + (size_t)(ct * 64 + fr) * ldb + k0 + fq * 8;
; #pragma unroll 4
;         for (int ks = 0; ks < nks; ++ks) {
;             bf16x8 a[4], b[4];
; #pragma unroll
;             for (int mi = 0; mi < 4; ++mi) a[mi] = *(const bf16x8*)(ap + (size_t)(mi * 16) * lda + ks * 32);
; #pragma unroll
;             for (int ni = 0; ni < 4; ++ni) { const int roff = PAIR ? ((ni & 1) * 16 + (ni >> 1) * 128) : ni * 16; b[ni] = *(const bf16x8*)(bp + (size_t)roff * ldb + ks * 32); }
; #pragma unroll
;             for (int mi = 0; mi < 4; ++mi)
; #pragma unroll
;                 for (int ni = 0; ni < 4; ++ni) acc[mi][ni] = __builtin_amdgcn_mfma_f32_16x16x32_bf16(b[ni], a[mi], acc[mi][ni], 0, 0, 0);
;         }
;         __syncthreads();
; #pragma unroll
;         for (int mi = 0; mi < 4; ++mi)
; #pragma unroll
;             for (int ni = 0; ni < 4; ++ni) *(LAS f32x4*)(red + (wid * 64 + mi * 16 + fr) * 68 + ni * 16 + 4 * fq) = acc[mi][ni];
;         __syncthreads();
.LBB0_749:
	s_ashr_i32 s6, s5, 31
	s_lshr_b32 s6, s6, 30
	s_add_i32 s6, s5, s6
	s_ashr_i32 s6, s6, 2
	s_lshl_b32 s7, s6, 6
	v_or_b32_e32 v18, s7, v4
	v_ashrrev_i32_e32 v19, 31, v18
	v_lshlrev_b64 v[18:19], 10, v[18:19]
	v_lshl_add_u64 v[22:23], v[2:3], 0, v[18:19]
	s_lshl_b32 s10, s6, 8
	v_add_co_u32_e32 v82, vcc, s3, v22
	s_sub_i32 s6, s1, s10
	s_nop 0
	v_addc_co_u32_e32 v83, vcc, 0, v23, vcc
	v_add_u32_e32 v20, s6, v4
	v_add_co_u32_e32 v90, vcc, s0, v22
	v_ashrrev_i32_e32 v21, 31, v20
	s_nop 0
	v_addc_co_u32_e32 v91, vcc, 0, v23, vcc
	v_lshlrev_b64 v[20:21], 10, v[20:21]
	v_add_co_u32_e32 v98, vcc, s4, v22
	v_lshl_add_u64 v[42:43], v[0:1], 0, v[20:21]
	s_nop 0
	v_addc_co_u32_e32 v99, vcc, 0, v23, vcc
	v_add_co_u32_e32 v54, vcc, s3, v42
	global_load_dwordx4 v[18:21], v[22:23], off
	s_nop 0
	v_addc_co_u32_e32 v55, vcc, 0, v43, vcc
	v_add_co_u32_e32 v66, vcc, s0, v42
	global_load_dwordx4 v[22:25], v[22:23], off offset:64
	s_nop 0
	global_load_dwordx4 v[26:29], v[42:43], off
	v_addc_co_u32_e32 v67, vcc, 0, v43, vcc
	v_add_co_u32_e32 v78, vcc, s4, v42
	s_add_i32 s5, s5, s92
	s_nop 0
	v_addc_co_u32_e32 v79, vcc, 0, v43, vcc
	global_load_dwordx4 v[30:33], v[82:83], off
	global_load_dwordx4 v[34:37], v[90:91], off
	global_load_dwordx4 v[38:41], v[98:99], off
	s_nop 0
	global_load_dwordx4 v[42:45], v[42:43], off offset:64
	s_nop 0
	global_load_dwordx4 v[50:53], v[54:55], off
	s_nop 0
	global_load_dwordx4 v[54:57], v[54:55], off offset:64
	s_nop 0
	global_load_dwordx4 v[62:65], v[66:67], off
	s_nop 0
	global_load_dwordx4 v[66:69], v[66:67], off offset:64
	s_nop 0
	global_load_dwordx4 v[74:77], v[78:79], off
	s_nop 0
	global_load_dwordx4 v[78:81], v[78:79], off offset:64
	s_add_i32 s1, s1, s48
	global_load_dwordx4 v[82:85], v[82:83], off offset:64
	s_cmp_lt_i32 s5, 32
	global_load_dwordx4 v[90:93], v[90:91], off offset:64
	s_waitcnt vmcnt(12)
	v_mfma_f32_16x16x32_bf16 v[46:49], v[18:21], v[26:29], 0
	global_load_dwordx4 v[98:101], v[98:99], off offset:64
	s_barrier
	s_waitcnt vmcnt(8)
	v_mfma_f32_16x16x32_bf16 v[58:61], v[18:21], v[50:53], 0
	s_waitcnt vmcnt(6)
	v_mfma_f32_16x16x32_bf16 v[70:73], v[18:21], v[62:65], 0
	s_waitcnt vmcnt(4)
	v_mfma_f32_16x16x32_bf16 v[18:21], v[18:21], v[74:77], 0
	v_mfma_f32_16x16x32_bf16 v[86:89], v[30:33], v[26:29], 0
	v_mfma_f32_16x16x32_bf16 v[94:97], v[34:37], v[26:29], 0
	v_mfma_f32_16x16x32_bf16 v[26:29], v[38:41], v[26:29], 0
	v_mfma_f32_16x16x32_bf16 v[102:105], v[30:33], v[50:53], 0
	v_mfma_f32_16x16x32_bf16 v[106:109], v[34:37], v[50:53], 0
	v_mfma_f32_16x16x32_bf16 v[50:53], v[38:41], v[50:53], 0
	v_mfma_f32_16x16x32_bf16 v[110:113], v[30:33], v[62:65], 0
	v_mfma_f32_16x16x32_bf16 v[114:117], v[34:37], v[62:65], 0
	v_mfma_f32_16x16x32_bf16 v[62:65], v[38:41], v[62:65], 0
	v_mfma_f32_16x16x32_bf16 v[30:33], v[30:33], v[74:77], 0
	v_mfma_f32_16x16x32_bf16 v[34:37], v[34:37], v[74:77], 0
	v_mfma_f32_16x16x32_bf16 v[38:41], v[38:41], v[74:77], 0
	v_mfma_f32_16x16x32_bf16 v[46:49], v[22:25], v[42:45], v[46:49]
	v_mfma_f32_16x16x32_bf16 v[58:61], v[22:25], v[54:57], v[58:61]
	v_mfma_f32_16x16x32_bf16 v[70:73], v[22:25], v[66:69], v[70:73]
	s_waitcnt vmcnt(3)
	v_mfma_f32_16x16x32_bf16 v[18:21], v[22:25], v[78:81], v[18:21]
	s_waitcnt vmcnt(2)
	v_mfma_f32_16x16x32_bf16 v[22:25], v[82:85], v[42:45], v[86:89]
	s_waitcnt vmcnt(1)
	v_mfma_f32_16x16x32_bf16 v[74:77], v[90:93], v[42:45], v[94:97]
	s_waitcnt vmcnt(0)
	v_mfma_f32_16x16x32_bf16 v[26:29], v[98:101], v[42:45], v[26:29]
	v_mfma_f32_16x16x32_bf16 v[42:45], v[82:85], v[54:57], v[102:105]
	s_nop 2
	v_add_u32_e32 v104, s6, v5
	v_or_b32_e32 v102, s7, v6
	v_ashrrev_i32_e32 v105, 31, v104
	v_mfma_f32_16x16x32_bf16 v[86:89], v[90:93], v[54:57], v[106:109]
	v_ashrrev_i32_e32 v103, 31, v102
	v_mfma_f32_16x16x32_bf16 v[50:53], v[98:101], v[54:57], v[50:53]
	s_nop 0
	v_lshl_add_u64 v[106:107], v[102:103], 2, s[12:13]
	v_lshlrev_b64 v[102:103], 1, v[102:103]
	v_mfma_f32_16x16x32_bf16 v[54:57], v[82:85], v[66:69], v[110:113]
	v_mfma_f32_16x16x32_bf16 v[94:97], v[90:93], v[66:69], v[114:117]
	v_mfma_f32_16x16x32_bf16 v[62:65], v[98:101], v[66:69], v[62:65]
	v_lshlrev_b64 v[66:67], 10, v[104:105]
	v_lshl_add_u64 v[66:67], s[46:47], 0, v[66:67]
	v_lshl_add_u64 v[66:67], v[66:67], 0, v[102:103]
	v_mfma_f32_16x16x32_bf16 v[30:33], v[82:85], v[78:81], v[30:33]
	v_lshlrev_b64 v[68:69], 11, v[104:105]
	v_lshl_add_u64 v[68:69], s[8:9], 0, v[68:69]
	v_lshl_add_u64 v[102:103], v[68:69], 0, v[102:103]
	v_mfma_f32_16x16x32_bf16 v[34:37], v[90:93], v[78:81], v[34:37]
	v_mfma_f32_16x16x32_bf16 v[38:41], v[98:101], v[78:81], v[38:41]
	ds_write_b128 v16, v[46:49]
	ds_write_b128 v16, v[58:61] offset:4352
	ds_write_b128 v16, v[70:73] offset:8704
	ds_write_b128 v16, v[18:21] offset:13056
	ds_write_b128 v16, v[22:25] offset:64
	ds_write_b128 v16, v[74:77] offset:128
	ds_write_b128 v16, v[26:29] offset:192
	ds_write_b128 v16, v[42:45] offset:4416
	ds_write_b128 v16, v[86:89] offset:4480
	ds_write_b128 v16, v[50:53] offset:4544
	ds_write_b128 v16, v[54:57] offset:8768
	ds_write_b128 v16, v[94:97] offset:8832
	ds_write_b128 v16, v[62:65] offset:8896
	ds_write_b128 v16, v[30:33] offset:13120
	ds_write_b128 v16, v[34:37] offset:13184
	ds_write_b128 v16, v[38:41] offset:13248
	s_waitcnt lgkmcnt(0)
	s_barrier
; #define LAS __attribute__((address_space(3)))
; __device__ __forceinline__ float sigmoidf_(float x) { return __builtin_amdgcn_rcpf(1.f + __builtin_amdgcn_exp2f(-1.4426950408889634f * x)); }
; __device__ __forceinline__ u32x4 pack8(const f32x4 a, const f32x4 b) { u32x4 w; w.x = cvt_pk_bf16(a[0], a[1]); w.y = cvt_pk_bf16(a[2], a[3]); w.z = cvt_pk_bf16(b[0], b[1]); w.w = cvt_pk_bf16(b[2], b[3]); return w; }
; __device__ __forceinline__ void unpack8(const u32x4 w, f32x4& a, f32x4& b) { a = (f32x4){bf_lo(w.x), bf_hi(w.x), bf_lo(w.y), bf_hi(w.y)}; b = (f32x4){bf_lo(w.z), bf_hi(w.z), bf_lo(w.w), bf_hi(w.w)}; }
;     __device__ __forceinline__ void small(size_t row, int col, const f32x4 v0, const f32x4 v1) const { *(u32x4*)(Ub + row * DSSM + col) = pack8(v0, v1); }
;     __device__ __forceinline__ void piece(size_t row, int col, f32x4 v0, f32x4 v1, const f32x4 b0, const f32x4 b1) const {
;     ...
;         if constexpr (MODE == 4) { f32x4 r0, r1; unpack8(*(const u32x4*)(res + row * ldr + col), r0, r1); v0 = v0 + b0; v1 = v1 + b1;
; #pragma unroll
;             for (int e = 0; e < 4; ++e) { v0[e] = r0[e] * sigmoidf_(v0[e]); v1[e] = r1[e] * sigmoidf_(v1[e]); }
;             *(u32x4*)((bf16_t*)O + row * ldo + col) = pack8(v0, v1); }
;     }
;     __device__ __forceinline__ void small(size_t row, int col, const f32x4 v0, const f32x4 v1) const {
;         const f32x4 z = (f32x4){0.f, 0.f, 0.f, 0.f};
;         piece(row, col, v0, v1, (MODE >= 2) ? *(const f32x4*)(bias + col) : z, (MODE >= 2) ? *(const f32x4*)(bias + col + 4) : z);
;     }
; template <class Epi, bool PAIR>
; __device__ __forceinline__ void small_gemm(LAS unsigned char* lds, const bf16_t* A, int lda, const bf16_t* B, int ldb, int K, int nrg, int nct, size_t row_base, int col_base, const Epi& E, int G, int c) {
;     ...
;         if constexpr (!PAIR) {
;             const int r = tid >> 3, pc = tid & 7; f32x4 v0 = (f32x4){0.f, 0.f, 0.f, 0.f}, v1 = v0;
; #pragma unroll
;             for (int w = 0; w < 8; ++w) { v0 += *(const LAS f32x4*)(red + (w * 64 + r) * 68 + pc * 8); v1 += *(const LAS f32x4*)(red + (w * 64 + r) * 68 + pc * 8 + 4); }
;             E.small(row_base + rg * 64 + r, col_base + ct * 64 + pc * 8, v0, v1);
	global_load_dwordx4 v[18:21], v[66:67], off
	global_load_dwordx4 v[22:25], v[106:107], off
	global_load_dwordx4 v[26:29], v[106:107], off offset:16
	ds_read_b128 v[30:33], v7
	ds_read_b128 v[34:37], v7 offset:16
	ds_read_b128 v[38:41], v7 offset:17408
	ds_read_b128 v[42:45], v7 offset:17424
	ds_read_b128 v[46:49], v7 offset:34816
	ds_read_b128 v[50:53], v7 offset:34832
	ds_read_b128 v[54:57], v7 offset:52224
	ds_read_b128 v[58:61], v7 offset:52240
	ds_read_b128 v[62:65], v8
	ds_read_b128 v[66:69], v9
	ds_read_b128 v[70:73], v10
	ds_read_b128 v[74:77], v11
	ds_read_b128 v[78:81], v12
	ds_read_b128 v[82:85], v13
	ds_read_b128 v[86:89], v14
	ds_read_b128 v[90:93], v15
	s_waitcnt lgkmcnt(14)
	v_pk_add_f32 v[32:33], v[32:33], 0 op_sel_hi:[1,0]
	v_pk_add_f32 v[30:31], v[30:31], 0 op_sel_hi:[1,0]
	v_pk_add_f32 v[34:35], v[34:35], 0 op_sel_hi:[1,0]
	v_pk_add_f32 v[36:37], v[36:37], 0 op_sel_hi:[1,0]
	s_waitcnt lgkmcnt(13)
	v_pk_add_f32 v[32:33], v[32:33], v[40:41]
	v_pk_add_f32 v[30:31], v[30:31], v[38:39]
	s_waitcnt lgkmcnt(12)
	v_pk_add_f32 v[34:35], v[34:35], v[42:43]
	v_pk_add_f32 v[36:37], v[36:37], v[44:45]
	s_waitcnt lgkmcnt(11)
	v_pk_add_f32 v[32:33], v[32:33], v[48:49]
	v_pk_add_f32 v[30:31], v[30:31], v[46:47]
	s_waitcnt lgkmcnt(10)
	v_pk_add_f32 v[34:35], v[34:35], v[50:51]
	v_pk_add_f32 v[36:37], v[36:37], v[52:53]
	s_waitcnt lgkmcnt(9)
	v_pk_add_f32 v[32:33], v[32:33], v[56:57]
	v_pk_add_f32 v[30:31], v[30:31], v[54:55]
	s_waitcnt lgkmcnt(8)
	v_pk_add_f32 v[34:35], v[34:35], v[58:59]
	v_pk_add_f32 v[36:37], v[36:37], v[60:61]
	s_waitcnt lgkmcnt(7)
	v_pk_add_f32 v[32:33], v[32:33], v[64:65]
	v_pk_add_f32 v[30:31], v[30:31], v[62:63]
	s_waitcnt lgkmcnt(6)
	v_pk_add_f32 v[34:35], v[34:35], v[66:67]
	v_pk_add_f32 v[36:37], v[36:37], v[68:69]
	s_waitcnt lgkmcnt(5)
	v_pk_add_f32 v[32:33], v[32:33], v[72:73]
	v_pk_add_f32 v[30:31], v[30:31], v[70:71]
	s_waitcnt lgkmcnt(4)
	v_pk_add_f32 v[34:35], v[34:35], v[74:75]
	v_pk_add_f32 v[36:37], v[36:37], v[76:77]
	s_waitcnt lgkmcnt(3)
	v_pk_add_f32 v[32:33], v[32:33], v[80:81]
	v_pk_add_f32 v[30:31], v[30:31], v[78:79]
	s_waitcnt lgkmcnt(2)
	v_pk_add_f32 v[34:35], v[34:35], v[82:83]
	v_pk_add_f32 v[36:37], v[36:37], v[84:85]
	s_waitcnt lgkmcnt(1)
	v_pk_add_f32 v[32:33], v[32:33], v[88:89]
	v_pk_add_f32 v[30:31], v[30:31], v[86:87]
	s_waitcnt lgkmcnt(0)
	v_pk_add_f32 v[34:35], v[34:35], v[90:91]
	v_pk_add_f32 v[36:37], v[36:37], v[92:93]
	s_waitcnt vmcnt(2)
	v_lshlrev_b32_e32 v17, 16, v18
	v_and_b32_e32 v38, 0xffff0000, v18
	v_lshlrev_b32_e32 v39, 16, v19
	v_and_b32_e32 v40, 0xffff0000, v19
	v_lshlrev_b32_e32 v41, 16, v20
	v_and_b32_e32 v42, 0xffff0000, v20
	v_lshlrev_b32_e32 v43, 16, v21
	v_and_b32_e32 v44, 0xffff0000, v21
	s_waitcnt vmcnt(1)
	v_pk_add_f32 v[18:19], v[32:33], v[24:25]
	v_pk_add_f32 v[20:21], v[30:31], v[22:23]
	s_waitcnt vmcnt(0)
	v_pk_add_f32 v[24:25], v[34:35], v[26:27]
	v_pk_add_f32 v[22:23], v[36:37], v[28:29]
	v_mul_f32_e32 v20, 0xbfb8aa3b, v20
	v_mul_f32_e32 v24, 0xbfb8aa3b, v24
	v_mul_f32_e32 v21, 0xbfb8aa3b, v21
	v_mul_f32_e32 v19, 0xbfb8aa3b, v19
	v_mul_f32_e32 v25, 0xbfb8aa3b, v25
	v_mul_f32_e32 v18, 0xbfb8aa3b, v18
	v_mul_f32_e32 v22, 0xbfb8aa3b, v22
	v_mul_f32_e32 v23, 0xbfb8aa3b, v23
	v_exp_f32_e32 v20, v20
	v_exp_f32_e32 v24, v24
	v_exp_f32_e32 v21, v21
	v_exp_f32_e32 v19, v19
	v_exp_f32_e32 v25, v25
	v_exp_f32_e32 v18, v18
	v_exp_f32_e32 v22, v22
	v_exp_f32_e32 v23, v23
	v_add_f32_e32 v20, 1.0, v20
	v_add_f32_e32 v24, 1.0, v24
	v_add_f32_e32 v21, 1.0, v21
	v_add_f32_e32 v19, 1.0, v19
	v_add_f32_e32 v25, 1.0, v25
	v_add_f32_e32 v18, 1.0, v18
	v_add_f32_e32 v22, 1.0, v22
	v_add_f32_e32 v23, 1.0, v23
	v_rcp_f32_e32 v20, v20
	v_rcp_f32_e32 v24, v24
	v_rcp_f32_e32 v21, v21
	v_rcp_f32_e32 v19, v19
	v_rcp_f32_e32 v25, v25
	v_rcp_f32_e32 v18, v18
	v_rcp_f32_e32 v22, v22
	v_rcp_f32_e32 v23, v23
	v_mul_f32_e32 v17, v20, v17
	v_mul_f32_e32 v20, v24, v41
	v_mul_f32_e32 v21, v21, v38
	v_mul_f32_e32 v19, v19, v40
	v_mul_f32_e32 v24, v25, v42
	v_mul_f32_e32 v25, v18, v39
	v_mul_f32_e32 v22, v22, v43
	v_mul_f32_e32 v23, v23, v44
	v_cvt_pk_bf16_f32 v18, v17, v21
	v_cvt_pk_bf16_f32 v19, v25, v19
	v_cvt_pk_bf16_f32 v20, v20, v24
	v_cvt_pk_bf16_f32 v21, v22, v23
	global_store_dwordx4 v[102:103], v[18:21], off sc0 sc1
	s_cbranch_scc1 .LBB0_749

; __device__ __forceinline__ unsigned xb_ld(unsigned* p)              { return __hip_atomic_load(p, __ATOMIC_RELAXED, __HIP_MEMORY_SCOPE_AGENT); }
; __device__ __forceinline__ unsigned xb_add(unsigned* p, unsigned v) { return __hip_atomic_fetch_add(p, v, __ATOMIC_RELAXED, __HIP_MEMORY_SCOPE_AGENT); }
; #define XB_SPIN(cond, bar) do { unsigned _sp = 0; while (cond) { __builtin_amdgcn_s_sleep(1); \
;     if ((++_sp & 255u) == 0u) { if (xb_ld(&(bar)[XB_TMO])) break; if (_sp > XB_SPIN_CAP) { atomicAdd(&(bar)[XB_TMO], 1u); break; } } } } while (0)
; __device__ __forceinline__ void xcd_barrier(const XcdBarrier& b) {
;     ...
;         const unsigned old = xb_add(&bar[XB_XSUB(b.x)], 1u);
;         const unsigned gen = old / nloc;
;         if (old + 1u == (gen + 1u) * nloc) {
;             __builtin_amdgcn_fence(__ATOMIC_RELEASE, "agent");
;             asm volatile("s_waitcnt vmcnt(0)" ::: "memory");
;             const unsigned og = xb_add(&bar[XB_TOP], 1u);
;             const unsigned tg = og / nx;
;             if (og + 1u == (tg + 1u) * nx) xb_add(&bar[XB_TOPGEN], 1u);
;             else XB_SPIN(xb_ld(&bar[XB_TOPGEN]) == tg, bar);
.LBB0_782:
	s_andn2_saveexec_b64 s[6:7], s[6:7]
	s_cbranch_execz .LBB0_802
	s_mov_b64 s[6:7], exec
	v_readlane_b32 s3, v255, 40
	s_cmp_eq_u32 s3, 0
	s_cbranch_scc1 .Lnowb_4
	buffer_wbl2 sc1
.Lnowb_4:
	s_waitcnt lgkmcnt(0)
	s_waitcnt vmcnt(0)
	v_mbcnt_lo_u32_b32 v1, s6, 0
	v_mbcnt_hi_u32_b32 v1, s7, v1
	v_cmp_eq_u32_e32 vcc, 0, v1
	s_and_saveexec_b64 s[10:11], vcc
	s_cbranch_execz .LBB0_785
	s_bcnt1_i32_b64 s3, s[6:7]
	v_mov_b32_e32 v2, 0x3000
	v_mov_b32_e32 v3, s3
	global_atomic_add v2, v2, v3, s[58:59] offset:1024 sc0

; template <class Epi, bool PAIR>
; __device__ __forceinline__ void small_gemm(LAS unsigned char* lds, const bf16_t* A, int lda, const bf16_t* B, int ldb, int K, int nrg, int nct, size_t row_base, int col_base, const Epi& E, int G, int c) {
;     ...
;         const bf16_t* ap = A + (size_t)(rg * 64 + fr) * lda + k0 + fq * 8;
;         const bf16_t* bp;
;         if (PAIR) { const int ch0 = 32 * ct; bp = B + (size_t)(DSSM + 256 * (ch0 >> 7) + (ch0 & 127) + fr) * ldb + k0 + fq * 8; }
;         else bp = B + (size_t)(ct * 64 + fr) * ldb + k0 + fq * 8;
; #pragma unroll 4
;         for (int ks = 0; ks < nks; ++ks) {
;             bf16x8 a[4], b[4];
; #pragma unroll
;             for (int mi = 0; mi < 4; ++mi) a[mi] = *(const bf16x8*)(ap + (size_t)(mi * 16) * lda + ks * 32);
; #pragma unroll
;             for (int ni = 0; ni < 4; ++ni) { const int roff = PAIR ? ((ni & 1) * 16 + (ni >> 1) * 128) : ni * 16; b[ni] = *(const bf16x8*)(bp + (size_t)roff * ldb + ks * 32); }
; #pragma unroll
;             for (int mi = 0; mi < 4; ++mi)
; #pragma unroll
;                 for (int ni = 0; ni < 4; ++ni) acc[mi][ni] = __builtin_amdgcn_mfma_f32_16x16x32_bf16(b[ni], a[mi], acc[mi][ni], 0, 0, 0);
;         }
.LBB0_847:
	s_ashr_i32 s0, s16, 31
	s_lshr_b32 s0, s0, 30
	s_add_i32 s0, s16, s0
	s_ashr_i32 s10, s0, 2
	s_lshl_b32 s0, s10, 8
	s_sub_i32 s11, s4, s0
	s_waitcnt lgkmcnt(1)
	v_add_u32_e32 v8, s11, v10
	s_waitcnt lgkmcnt(0)
	v_ashrrev_i32_e32 v9, 31, v8
	v_lshlrev_b64 v[8:9], 11, v[8:9]
	s_lshl_b32 s17, s10, 6
	v_lshl_add_u64 v[8:9], v[0:1], 0, v[8:9]
	v_or_b32_e32 v4, s17, v10
	v_add_co_u32_e64 v128, s[0:1], s3, v8
	v_ashrrev_i32_e32 v5, 31, v4
	s_nop 0
	v_addc_co_u32_e64 v129, s[0:1], 0, v9, s[0:1]
	v_lshlrev_b64 v[4:5], 11, v[4:5]
	v_add_co_u32_e64 v132, s[0:1], s5, v8
	v_lshl_add_u64 v[124:125], v[2:3], 0, v[4:5]
	s_nop 0
	v_addc_co_u32_e64 v133, s[0:1], 0, v9, s[0:1]
	v_add_co_u32_e64 v126, s[0:1], s3, v124
	global_load_dwordx4 v[4:7], v[124:125], off
	global_load_dwordx4 v[28:31], v[8:9], off
	v_addc_co_u32_e64 v127, s[0:1], 0, v125, s[0:1]
	v_add_co_u32_e64 v130, s[0:1], s5, v124
	global_load_dwordx4 v[32:35], v[128:129], off
	global_load_dwordx4 v[36:39], v[132:133], off
	v_addc_co_u32_e64 v131, s[0:1], 0, v125, s[0:1]
	v_add_co_u32_e64 v140, s[0:1], s7, v8
	s_waitcnt vmcnt(2)
	v_mfma_f32_16x16x32_bf16 v[56:59], v[4:7], v[28:31], 0
	v_addc_co_u32_e64 v141, s[0:1], 0, v9, s[0:1]
	v_add_co_u32_e64 v134, s[0:1], s7, v124
	global_load_dwordx4 v[40:43], v[126:127], off
	global_load_dwordx4 v[44:47], v[140:141], off
	global_load_dwordx4 v[48:51], v[124:125], off offset:64
	global_load_dwordx4 v[52:55], v[8:9], off offset:64
	v_addc_co_u32_e64 v135, s[0:1], 0, v125, s[0:1]
	global_load_dwordx4 v[60:63], v[130:131], off
	global_load_dwordx4 v[64:67], v[128:129], off offset:64
	global_load_dwordx4 v[72:75], v[132:133], off offset:64
	global_load_dwordx4 v[80:83], v[134:135], off
	global_load_dwordx4 v[84:87], v[140:141], off offset:64
	global_load_dwordx4 v[88:91], v[126:127], off offset:64
	global_load_dwordx4 v[96:99], v[130:131], off offset:64
	global_load_dwordx4 v[104:107], v[134:135], off offset:64
	s_waitcnt vmcnt(13)
	v_mfma_f32_16x16x32_bf16 v[68:71], v[4:7], v[32:35], 0
	v_cmp_lt_i32_e64 s[0:1], v24, v25
	s_waitcnt vmcnt(12)
	v_mfma_f32_16x16x32_bf16 v[76:79], v[4:7], v[36:39], 0
	s_waitcnt vmcnt(10)
	v_mfma_f32_16x16x32_bf16 v[4:7], v[4:7], v[44:47], 0
	v_mfma_f32_16x16x32_bf16 v[92:95], v[40:43], v[28:31], 0
	s_waitcnt vmcnt(7)
	v_mfma_f32_16x16x32_bf16 v[100:103], v[60:63], v[28:31], 0
	s_waitcnt vmcnt(4)
	v_mfma_f32_16x16x32_bf16 v[28:31], v[80:83], v[28:31], 0
	v_mfma_f32_16x16x32_bf16 v[108:111], v[40:43], v[32:35], 0
	v_mfma_f32_16x16x32_bf16 v[112:115], v[60:63], v[32:35], 0
	v_mfma_f32_16x16x32_bf16 v[32:35], v[80:83], v[32:35], 0
	v_mfma_f32_16x16x32_bf16 v[120:123], v[60:63], v[36:39], 0
	v_mfma_f32_16x16x32_bf16 v[60:63], v[60:63], v[44:47], 0
	v_mfma_f32_16x16x32_bf16 v[116:119], v[40:43], v[36:39], 0
	v_mfma_f32_16x16x32_bf16 v[36:39], v[80:83], v[36:39], 0
	v_mfma_f32_16x16x32_bf16 v[40:43], v[40:43], v[44:47], 0
	v_mfma_f32_16x16x32_bf16 v[44:47], v[80:83], v[44:47], 0
	v_mfma_f32_16x16x32_bf16 v[56:59], v[48:51], v[52:55], v[56:59]
	v_mfma_f32_16x16x32_bf16 v[68:71], v[48:51], v[64:67], v[68:71]
	s_waitcnt vmcnt(2)
	v_mfma_f32_16x16x32_bf16 v[80:83], v[88:91], v[52:55], v[92:95]
	s_waitcnt vmcnt(1)
	v_mfma_f32_16x16x32_bf16 v[92:95], v[96:99], v[52:55], v[100:103]
	s_waitcnt vmcnt(0)
	v_mfma_f32_16x16x32_bf16 v[28:31], v[104:107], v[52:55], v[28:31]
	v_mfma_f32_16x16x32_bf16 v[52:55], v[88:91], v[64:67], v[108:111]
	v_mfma_f32_16x16x32_bf16 v[100:103], v[96:99], v[64:67], v[112:115]
	v_mfma_f32_16x16x32_bf16 v[32:35], v[104:107], v[64:67], v[32:35]
	v_mfma_f32_16x16x32_bf16 v[64:67], v[48:51], v[72:75], v[76:79]
	v_mfma_f32_16x16x32_bf16 v[4:7], v[48:51], v[84:87], v[4:7]
	v_mfma_f32_16x16x32_bf16 v[48:51], v[96:99], v[84:87], v[60:63]
	s_nop 2
	global_load_dwordx4 v[60:63], v[124:125], off offset:128
	v_mfma_f32_16x16x32_bf16 v[76:79], v[88:91], v[72:75], v[116:119]
	v_mfma_f32_16x16x32_bf16 v[108:111], v[96:99], v[72:75], v[120:123]
	v_mfma_f32_16x16x32_bf16 v[36:39], v[104:107], v[72:75], v[36:39]
	v_mfma_f32_16x16x32_bf16 v[40:43], v[88:91], v[84:87], v[40:43]
	v_mfma_f32_16x16x32_bf16 v[44:47], v[104:107], v[84:87], v[44:47]
	global_load_dwordx4 v[72:75], v[8:9], off offset:128
	global_load_dwordx4 v[84:87], v[8:9], off offset:192
	global_load_dwordx4 v[88:91], v[124:125], off offset:192
	global_load_dwordx4 v[96:99], v[126:127], off offset:128
	global_load_dwordx4 v[104:107], v[126:127], off offset:192
	global_load_dwordx4 v[112:115], v[130:131], off offset:128
	global_load_dwordx4 v[116:119], v[130:131], off offset:192
	global_load_dwordx4 v[120:123], v[134:135], off offset:128
	s_nop 0
	global_load_dwordx4 v[124:127], v[134:135], off offset:192
	s_waitcnt vmcnt(8)
	v_mfma_f32_16x16x32_bf16 v[56:59], v[60:63], v[72:75], v[56:59]
	s_waitcnt vmcnt(5)
	v_mfma_f32_16x16x32_bf16 v[80:83], v[96:99], v[72:75], v[80:83]
	s_waitcnt vmcnt(3)
	v_mfma_f32_16x16x32_bf16 v[92:95], v[112:115], v[72:75], v[92:95]
	s_waitcnt vmcnt(1)
	v_mfma_f32_16x16x32_bf16 v[28:31], v[120:123], v[72:75], v[28:31]
	global_load_dwordx4 v[72:75], v[128:129], off offset:128
	s_nop 0
	global_load_dwordx4 v[128:131], v[128:129], off offset:192
	s_waitcnt vmcnt(1)
	v_mfma_f32_16x16x32_bf16 v[68:71], v[60:63], v[72:75], v[68:71]
	v_mfma_f32_16x16x32_bf16 v[52:55], v[96:99], v[72:75], v[52:55]
	v_mfma_f32_16x16x32_bf16 v[100:103], v[112:115], v[72:75], v[100:103]
	v_mfma_f32_16x16x32_bf16 v[32:35], v[120:123], v[72:75], v[32:35]
	global_load_dwordx4 v[72:75], v[132:133], off offset:128
	s_nop 0
	global_load_dwordx4 v[132:135], v[132:133], off offset:192
	s_nop 0
	global_load_dwordx4 v[136:139], v[140:141], off offset:128
	s_waitcnt vmcnt(2)
	v_mfma_f32_16x16x32_bf16 v[64:67], v[60:63], v[72:75], v[64:67]
	v_mfma_f32_16x16x32_bf16 v[76:79], v[96:99], v[72:75], v[76:79]
	v_mfma_f32_16x16x32_bf16 v[108:111], v[112:115], v[72:75], v[108:111]
	v_mfma_f32_16x16x32_bf16 v[36:39], v[120:123], v[72:75], v[36:39]
	global_load_dwordx4 v[72:75], v[140:141], off offset:192
	s_barrier
; #define LAS __attribute__((address_space(3)))
; template <class Epi, bool PAIR>
; __device__ __forceinline__ void small_gemm(LAS unsigned char* lds, const bf16_t* A, int lda, const bf16_t* B, int ldb, int K, int nrg, int nct, size_t row_base, int col_base, const Epi& E, int G, int c) {
;     ...
;             for (int mi = 0; mi < 4; ++mi) a[mi] = *(const bf16x8*)(ap + (size_t)(mi * 16) * lda + ks * 32);
; #pragma unroll
;             for (int ni = 0; ni < 4; ++ni) { const int roff = PAIR ? ((ni & 1) * 16 + (ni >> 1) * 128) : ni * 16; b[ni] = *(const bf16x8*)(bp + (size_t)roff * ldb + ks * 32); }
; #pragma unroll
;             for (int mi = 0; mi < 4; ++mi)
; #pragma unroll
;                 for (int ni = 0; ni < 4; ++ni) acc[mi][ni] = __builtin_amdgcn_mfma_f32_16x16x32_bf16(b[ni], a[mi], acc[mi][ni], 0, 0, 0);
;         }
;         __syncthreads();
; #pragma unroll
;         for (int mi = 0; mi < 4; ++mi)
; #pragma unroll
;             for (int ni = 0; ni < 4; ++ni) *(LAS f32x4*)(red + (wid * 64 + mi * 16 + fr) * 68 + ni * 16 + 4 * fq) = acc[mi][ni];
;         __syncthreads();
	s_waitcnt vmcnt(1)
	v_mfma_f32_16x16x32_bf16 v[4:7], v[60:63], v[136:139], v[4:7]
	v_mfma_f32_16x16x32_bf16 v[40:43], v[96:99], v[136:139], v[40:43]
	v_mfma_f32_16x16x32_bf16 v[56:59], v[88:91], v[84:87], v[56:59]
	v_mfma_f32_16x16x32_bf16 v[28:31], v[124:127], v[84:87], v[28:31]
	v_mfma_f32_16x16x32_bf16 v[48:51], v[112:115], v[136:139], v[48:51]
	v_mfma_f32_16x16x32_bf16 v[60:63], v[104:107], v[84:87], v[80:83]
	v_mfma_f32_16x16x32_bf16 v[80:83], v[116:119], v[84:87], v[92:95]
	s_nop 3
	ds_write_b128 v22, v[56:59]
	s_nop 1
	ds_write_b128 v22, v[60:63] offset:64
	ds_write_b128 v22, v[80:83] offset:128
	v_mfma_f32_16x16x32_bf16 v[68:71], v[88:91], v[128:131], v[68:71]
	v_mfma_f32_16x16x32_bf16 v[84:87], v[116:119], v[128:131], v[100:103]
	v_mfma_f32_16x16x32_bf16 v[52:55], v[104:107], v[128:131], v[52:55]
	ds_write_b128 v22, v[28:31] offset:192
	s_nop 4
	ds_write_b128 v22, v[68:71] offset:4352
	s_nop 0
	ds_write_b128 v22, v[52:55] offset:4416
	v_mfma_f32_16x16x32_bf16 v[32:35], v[124:127], v[128:131], v[32:35]
	v_mfma_f32_16x16x32_bf16 v[44:47], v[120:123], v[136:139], v[44:47]
	v_mfma_f32_16x16x32_bf16 v[64:67], v[88:91], v[132:135], v[64:67]
	ds_write_b128 v22, v[84:87] offset:4480
	s_nop 4
	ds_write_b128 v22, v[32:35] offset:4544
	s_nop 0
	ds_write_b128 v22, v[64:67] offset:8704
	v_mfma_f32_16x16x32_bf16 v[76:79], v[104:107], v[132:135], v[76:79]
	s_waitcnt vmcnt(0)
	v_mfma_f32_16x16x32_bf16 v[4:7], v[88:91], v[72:75], v[4:7]
	v_mfma_f32_16x16x32_bf16 v[92:95], v[116:119], v[132:135], v[108:111]
	v_mfma_f32_16x16x32_bf16 v[28:31], v[104:107], v[72:75], v[40:43]
	v_mfma_f32_16x16x32_bf16 v[36:39], v[124:127], v[132:135], v[36:39]
	s_nop 2
	ds_write_b128 v22, v[76:79] offset:8768
	s_nop 1
	ds_write_b128 v22, v[92:95] offset:8832
	s_nop 0
	ds_write_b128 v22, v[36:39] offset:8896
	v_mfma_f32_16x16x32_bf16 v[32:35], v[116:119], v[72:75], v[48:51]
	ds_write_b128 v22, v[4:7] offset:13056
	ds_write_b128 v22, v[28:31] offset:13120
	s_nop 5
	ds_write_b128 v22, v[32:35] offset:13184
	v_mfma_f32_16x16x32_bf16 v[4:7], v[124:127], v[72:75], v[44:47]
	s_nop 7
	ds_write_b128 v22, v[4:7] offset:13248
	v_add_u32_e32 v4, s11, v11
	v_ashrrev_i32_e32 v5, 31, v4
	v_or_b32_e32 v6, s17, v12
	v_lshlrev_b64 v[40:41], 11, v[4:5]
	v_ashrrev_i32_e32 v7, 31, v6
	v_lshl_add_u64 v[8:9], s[44:45], 0, v[40:41]
	v_lshlrev_b64 v[42:43], 1, v[6:7]
	v_lshl_add_u64 v[6:7], v[8:9], 0, v[42:43]
	s_waitcnt lgkmcnt(0)
	s_barrier
;     __device__ __forceinline__ void piece(size_t row, int col, f32x4 v0, f32x4 v1, const f32x4 a0, const f32x4 a1, const f32x4 b0, const f32x4 b1, const f32x4 c0, const f32x4 c1,
;                                           float mean, float rstd, float& s, float& ss) const {
;         if constexpr (MODE == 1) { f32x4 r0, r1; unpack8(*(const u32x4*)(Tin + row * DM + col), r0, r1); v0 = r0 * ALPHA + v0; v1 = r1 * ALPHA + v1; }
;         if constexpr (MODE == 2) { v0 = ((v0 - a0 * mean) * rstd + b0) * scale; v1 = ((v1 - a1 * mean) * rstd + b1) * scale; }
;         if constexpr (RECOMP) { f32x4 r0, r1; unpack8(*(const u32x4*)(Tin + row * DM + col), r0, r1);
;             r0 = (r0 - mean) * rstd * a0 + b0; r1 = (r1 - mean) * rstd * a1 + b1; v0 = r0 * ALPHA + v0; v1 = r1 * ALPHA + v1;
;             if constexpr (MODE == 5) { v0 = v0 + c0; v1 = v1 + c1; } }
;         if constexpr (MODE == 4) { v0 = (v0 - a0 * mean) * rstd + b0; v1 = (v1 - a1 * mean) * rstd + b1;
; #pragma unroll
;             for (int e = 0; e < 4; ++e) { const float x = fmaxf(v0[e], 0.f), y = fmaxf(v1[e], 0.f); v0[e] = x * x; v1[e] = y * y; } }
;         if constexpr (PROD) {
; #pragma unroll
;             for (int e = 0; e < 4; ++e) { s += v0[e] + v1[e]; ss += v0[e] * v0[e] + v1[e] * v1[e]; } }
;     __device__ __forceinline__ void small(size_t row, int col, const f32x4 v0, const f32x4 v1) const {
;         const f32x4 z = (f32x4){0.f, 0.f, 0.f, 0.f};
;         float mean = 0.f, rstd = 0.f;
;         if constexpr (CONS) { float s0, q0, s1, q1; stats_of(st_in, row, 0, s0, q0); stats_of(st_in, row, 1, s1, q1); mean = (s0 + s1) * (1.f / DM); rstd = __builtin_amdgcn_rsqf(fmaxf((q0 + q1) * (1.f / DM) - mean * mean, 0.f) + LN_EPS); }
;         float s = 0.f, ss = 0.f;
;         piece(row, col, v0, v1, CONS ? *(const f32x4*)(va + col) : z, CONS ? *(const f32x4*)(va + col + 4) : z, CONS ? *(const f32x4*)(vb + col) : z, CONS ? *(const f32x4*)(vb + col + 4) : z,
;               (MODE == 5) ? *(const f32x4*)(bias + col) : z, (MODE == 5) ? *(const f32x4*)(bias + col + 4) : z, mean, rstd, s, ss);
;         if constexpr (PROD) { s += __shfl_xor(s, 1); ss += __shfl_xor(ss, 1); s += __shfl_xor(s, 2); ss += __shfl_xor(ss, 2); s += __shfl_xor(s, 4); ss += __shfl_xor(ss, 4);
;             if ((threadIdx.x & 7) == 0) st_out[row * 16 + (col >> 6)] = (f32x2){s, ss}; }
	global_load_dwordx4 v[6:9], v[6:7], off
	ds_read_b128 v[28:31], v13
	ds_read_b128 v[32:35], v13 offset:16
	ds_read_b128 v[36:39], v13 offset:17408
	s_waitcnt lgkmcnt(2)
	v_pk_add_f32 v[44:45], v[30:31], 0 op_sel_hi:[1,0]
	v_pk_add_f32 v[46:47], v[28:29], 0 op_sel_hi:[1,0]
	ds_read_b128 v[28:31], v13 offset:17424
	s_waitcnt lgkmcnt(2)
	v_pk_add_f32 v[48:49], v[34:35], 0 op_sel_hi:[1,0]
	v_pk_add_f32 v[50:51], v[32:33], 0 op_sel_hi:[1,0]
	ds_read_b128 v[32:35], v13 offset:34816
	s_waitcnt lgkmcnt(2)
	v_pk_add_f32 v[44:45], v[44:45], v[38:39]
	v_pk_add_f32 v[46:47], v[46:47], v[36:37]
	s_waitcnt lgkmcnt(1)
	v_pk_add_f32 v[48:49], v[48:49], v[30:31]
	ds_read_b128 v[36:39], v13 offset:34832
	v_pk_add_f32 v[50:51], v[50:51], v[28:29]
	ds_read_b128 v[28:31], v13 offset:52224
	s_waitcnt lgkmcnt(2)
	v_pk_add_f32 v[44:45], v[44:45], v[34:35]
	v_pk_add_f32 v[46:47], v[46:47], v[32:33]
	ds_read_b128 v[32:35], v13 offset:52240
	s_waitcnt lgkmcnt(2)
	v_pk_add_f32 v[48:49], v[48:49], v[38:39]
	v_pk_add_f32 v[50:51], v[50:51], v[36:37]
	s_waitcnt lgkmcnt(1)
	v_pk_add_f32 v[44:45], v[44:45], v[30:31]
	ds_read_b128 v[36:39], v14
	v_pk_add_f32 v[46:47], v[46:47], v[28:29]
	ds_read_b128 v[28:31], v15
	s_waitcnt lgkmcnt(2)
	v_pk_add_f32 v[48:49], v[48:49], v[34:35]
	v_pk_add_f32 v[50:51], v[50:51], v[32:33]
	ds_read_b128 v[32:35], v16
	s_waitcnt lgkmcnt(2)
	v_pk_add_f32 v[44:45], v[44:45], v[38:39]
	v_pk_add_f32 v[46:47], v[46:47], v[36:37]
	s_waitcnt lgkmcnt(1)
	v_pk_add_f32 v[48:49], v[48:49], v[30:31]
	ds_read_b128 v[36:39], v17
	v_pk_add_f32 v[50:51], v[50:51], v[28:29]
	ds_read_b128 v[28:31], v18
	s_waitcnt lgkmcnt(2)
	v_pk_add_f32 v[44:45], v[44:45], v[34:35]
	v_pk_add_f32 v[46:47], v[46:47], v[32:33]
	ds_read_b128 v[32:35], v19
	s_waitcnt lgkmcnt(2)
	v_pk_add_f32 v[48:49], v[48:49], v[38:39]
	v_pk_add_f32 v[50:51], v[50:51], v[36:37]
	s_waitcnt lgkmcnt(1)
	v_pk_add_f32 v[44:45], v[44:45], v[30:31]
	ds_read_b128 v[36:39], v20
	v_pk_add_f32 v[46:47], v[46:47], v[28:29]
	ds_read_b128 v[28:31], v21
	s_waitcnt lgkmcnt(2)
	v_pk_add_f32 v[32:33], v[50:51], v[32:33]
	v_pk_add_f32 v[34:35], v[48:49], v[34:35]
	s_waitcnt lgkmcnt(1)
	v_pk_add_f32 v[36:37], v[46:47], v[36:37]
	v_pk_add_f32 v[38:39], v[44:45], v[38:39]
	s_waitcnt lgkmcnt(0)
	v_pk_add_f32 v[28:29], v[32:33], v[28:29]
	v_pk_add_f32 v[30:31], v[34:35], v[30:31]
	s_waitcnt vmcnt(0)
	v_lshlrev_b32_e32 v32, 16, v6
	v_and_b32_e32 v33, 0xffff0000, v6
	v_lshlrev_b32_e32 v34, 16, v8
	v_and_b32_e32 v35, 0xffff0000, v8
	v_lshlrev_b32_e32 v8, 16, v9
	v_and_b32_e32 v9, 0xffff0000, v9
	v_pk_fma_f32 v[32:33], v[32:33], s[6:7], v[36:37] op_sel_hi:[1,0,1]
	v_pk_fma_f32 v[36:37], v[8:9], s[6:7], v[30:31] op_sel_hi:[1,0,1]
	v_pk_fma_f32 v[8:9], v[34:35], s[6:7], v[28:29] op_sel_hi:[1,0,1]
	v_pk_mul_f32 v[30:31], v[32:33], v[32:33]
	v_lshlrev_b32_e32 v6, 16, v7
	v_and_b32_e32 v7, 0xffff0000, v7
	v_pk_fma_f32 v[30:31], v[8:9], v[8:9], v[30:31]
	v_pk_fma_f32 v[6:7], v[6:7], s[6:7], v[38:39] op_sel_hi:[1,0,1]
	v_pk_add_f32 v[30:31], v[30:31], v[30:31] op_sel_hi:[1,0]
	v_mov_b32_e32 v34, v6
	v_mov_b32_e32 v35, v36
	v_mul_f32_e32 v30, v6, v6
	v_pk_fma_f32 v[34:35], v[34:35], v[34:35], v[30:31] op_sel_hi:[1,1,0]
	v_cndmask_b32_e64 v30, v23, v24, s[0:1]
	v_pk_add_f32 v[28:29], v[32:33], v[8:9]
	v_lshlrev_b32_e32 v44, 2, v30
	v_mov_b32_e32 v34, v7
	v_mov_b32_e32 v30, v37
	v_add_f32_e32 v28, 0, v28
	v_pk_add_f32 v[30:31], v[34:35], v[30:31]
	v_pk_add_f32 v[34:35], v[6:7], v[36:37]
	v_pk_mul_f32 v[38:39], v[6:7], v[6:7]
	v_add_f32_e32 v28, v29, v28
	v_mul_f32_e32 v29, v37, v37
	v_mov_b32_e32 v35, v39
	v_pk_add_f32 v[28:29], v[34:35], v[28:29]
	v_cmp_lt_i32_e64 s[0:1], v26, v25
	v_pk_add_f32 v[28:29], v[28:29], v[30:31]
	ds_bpermute_b32 v30, v44, v28
	ds_bpermute_b32 v31, v44, v29
	v_cndmask_b32_e64 v34, v23, v26, s[0:1]
	v_lshlrev_b32_e32 v39, 2, v34
	v_cmp_lt_i32_e64 s[0:1], v27, v25
	s_waitcnt lgkmcnt(0)
	v_pk_add_f32 v[34:35], v[28:29], v[30:31]
	ds_bpermute_b32 v38, v39, v34
	ds_bpermute_b32 v39, v39, v35
	v_cvt_pk_bf16_f32 v30, v8, v9
	v_cndmask_b32_e64 v8, v23, v27, s[0:1]
	v_cvt_pk_bf16_f32 v29, v6, v7
	v_lshlrev_b32_e32 v9, 2, v8
	s_waitcnt lgkmcnt(0)
	v_pk_add_f32 v[6:7], v[34:35], v[38:39]
	ds_bpermute_b32 v8, v9, v6
	ds_bpermute_b32 v9, v9, v7
	v_cvt_pk_bf16_f32 v28, v32, v33
	v_lshl_add_u64 v[32:33], s[60:61], 0, v[40:41]
	v_lshl_add_u64 v[32:33], v[32:33], 0, v[42:43]
	v_cvt_pk_bf16_f32 v31, v36, v37
	global_store_dwordx4 v[32:33], v[28:31], off sc0 sc1
	s_and_saveexec_b64 s[0:1], vcc
	s_cbranch_execz .LBB0_846
	v_lshlrev_b64 v[4:5], 7, v[4:5]
	s_ashr_i32 s11, s10, 31
	v_lshl_add_u64 v[4:5], s[14:15], 0, v[4:5]
	s_waitcnt lgkmcnt(0)
	v_pk_add_f32 v[6:7], v[6:7], v[8:9]
	v_lshl_add_u64 v[4:5], s[10:11], 3, v[4:5]
	global_store_dwordx2 v[4:5], v[6:7], off sc0 sc1
	s_branch .LBB0_846

; __device__ __forceinline__ unsigned xb_ld(unsigned* p)              { return __hip_atomic_load(p, __ATOMIC_RELAXED, __HIP_MEMORY_SCOPE_AGENT); }
; __device__ __forceinline__ unsigned xb_add(unsigned* p, unsigned v) { return __hip_atomic_fetch_add(p, v, __ATOMIC_RELAXED, __HIP_MEMORY_SCOPE_AGENT); }
; #define XB_SPIN(cond, bar) do { unsigned _sp = 0; while (cond) { __builtin_amdgcn_s_sleep(1); \
;     if ((++_sp & 255u) == 0u) { if (xb_ld(&(bar)[XB_TMO])) break; if (_sp > XB_SPIN_CAP) { atomicAdd(&(bar)[XB_TMO], 1u); break; } } } } while (0)
; __device__ __forceinline__ void xcd_barrier(const XcdBarrier& b) {
;     ...
;         const unsigned old = xb_add(&bar[XB_XSUB(b.x)], 1u);
;         const unsigned gen = old / nloc;
;         if (old + 1u == (gen + 1u) * nloc) {
;             __builtin_amdgcn_fence(__ATOMIC_RELEASE, "agent");
;             asm volatile("s_waitcnt vmcnt(0)" ::: "memory");
;             const unsigned og = xb_add(&bar[XB_TOP], 1u);
;             const unsigned tg = og / nx;
;             if (og + 1u == (tg + 1u) * nx) xb_add(&bar[XB_TOPGEN], 1u);
;             else XB_SPIN(xb_ld(&bar[XB_TOPGEN]) == tg, bar);
.LBB0_881:
	s_andn2_saveexec_b64 s[4:5], s[10:11]
	s_cbranch_execz .LBB0_901
	s_mov_b64 s[10:11], exec
	v_readlane_b32 s3, v255, 40
	s_cmp_eq_u32 s3, 0
	s_cbranch_scc1 .Lnowb_5
	buffer_wbl2 sc1
.Lnowb_5:
	s_waitcnt lgkmcnt(0)
	s_waitcnt vmcnt(0)
	v_mbcnt_lo_u32_b32 v1, s10, 0
	v_mbcnt_hi_u32_b32 v1, s11, v1
	v_cmp_eq_u32_e32 vcc, 0, v1
	s_and_saveexec_b64 s[16:17], vcc
	s_cbranch_execz .LBB0_884
	s_bcnt1_i32_b64 s3, s[10:11]
	v_mov_b32_e32 v2, 0x3000
	v_mov_b32_e32 v3, s3
	global_atomic_add v2, v2, v3, s[58:59] offset:1024 sc0

; template <class Epi, bool PAIR>
; __device__ __forceinline__ void small_gemm(LAS unsigned char* lds, const bf16_t* A, int lda, const bf16_t* B, int ldb, int K, int nrg, int nct, size_t row_base, int col_base, const Epi& E, int G, int c) {
;     ...
;         const bf16_t* ap = A + (size_t)(rg * 64 + fr) * lda + k0 + fq * 8;
;         const bf16_t* bp;
;         if (PAIR) { const int ch0 = 32 * ct; bp = B + (size_t)(DSSM + 256 * (ch0 >> 7) + (ch0 & 127) + fr) * ldb + k0 + fq * 8; }
;         else bp = B + (size_t)(ct * 64 + fr) * ldb + k0 + fq * 8;
; #pragma unroll 4
;         for (int ks = 0; ks < nks; ++ks) {
;             bf16x8 a[4], b[4];
; #pragma unroll
;             for (int mi = 0; mi < 4; ++mi) a[mi] = *(const bf16x8*)(ap + (size_t)(mi * 16) * lda + ks * 32);
; #pragma unroll
;             for (int ni = 0; ni < 4; ++ni) { const int roff = PAIR ? ((ni & 1) * 16 + (ni >> 1) * 128) : ni * 16; b[ni] = *(const bf16x8*)(bp + (size_t)roff * ldb + ks * 32); }
; #pragma unroll
;             for (int mi = 0; mi < 4; ++mi)
; #pragma unroll
;                 for (int ni = 0; ni < 4; ++ni) acc[mi][ni] = __builtin_amdgcn_mfma_f32_16x16x32_bf16(b[ni], a[mi], acc[mi][ni], 0, 0, 0);
;         }
.LBB0_1283:
	s_ashr_i32 s0, s7, 31
	s_lshr_b32 s0, s0, 30
	s_add_i32 s0, s7, s0
	s_ashr_i32 s20, s0, 2
	s_lshl_b32 s0, s20, 8
	s_sub_i32 s11, s4, s0
	s_waitcnt lgkmcnt(1)
	v_add_u32_e32 v8, s11, v10
	s_waitcnt lgkmcnt(0)
	v_ashrrev_i32_e32 v9, 31, v8
	v_lshlrev_b64 v[8:9], 11, v[8:9]
	s_lshl_b32 s9, s20, 6
	v_lshl_add_u64 v[8:9], v[0:1], 0, v[8:9]
	v_or_b32_e32 v4, s9, v10
	v_add_co_u32_e64 v128, s[0:1], s3, v8
	v_ashrrev_i32_e32 v5, 31, v4
	s_nop 0
	v_addc_co_u32_e64 v129, s[0:1], 0, v9, s[0:1]
	v_lshlrev_b64 v[4:5], 11, v[4:5]
	v_add_co_u32_e64 v132, s[0:1], s5, v8
	v_lshl_add_u64 v[124:125], v[2:3], 0, v[4:5]
	s_nop 0
	v_addc_co_u32_e64 v133, s[0:1], 0, v9, s[0:1]
	v_add_co_u32_e64 v126, s[0:1], s3, v124
	global_load_dwordx4 v[4:7], v[124:125], off
	global_load_dwordx4 v[28:31], v[8:9], off
	v_addc_co_u32_e64 v127, s[0:1], 0, v125, s[0:1]
	v_add_co_u32_e64 v130, s[0:1], s5, v124
	global_load_dwordx4 v[32:35], v[128:129], off
	global_load_dwordx4 v[36:39], v[132:133], off
	v_addc_co_u32_e64 v131, s[0:1], 0, v125, s[0:1]
	v_add_co_u32_e64 v140, s[0:1], s6, v8
	v_readlane_b32 s68, v254, 3
	s_nop 0
	v_addc_co_u32_e64 v141, s[0:1], 0, v9, s[0:1]
	v_add_co_u32_e64 v134, s[0:1], s6, v124
	global_load_dwordx4 v[40:43], v[126:127], off
	global_load_dwordx4 v[44:47], v[140:141], off
	global_load_dwordx4 v[48:51], v[124:125], off offset:64
	global_load_dwordx4 v[52:55], v[8:9], off offset:64
	v_addc_co_u32_e64 v135, s[0:1], 0, v125, s[0:1]
	global_load_dwordx4 v[60:63], v[130:131], off
	global_load_dwordx4 v[64:67], v[128:129], off offset:64
	global_load_dwordx4 v[72:75], v[132:133], off offset:64
	global_load_dwordx4 v[80:83], v[134:135], off
	global_load_dwordx4 v[84:87], v[140:141], off offset:64
	global_load_dwordx4 v[88:91], v[126:127], off offset:64
	global_load_dwordx4 v[96:99], v[130:131], off offset:64
	global_load_dwordx4 v[104:107], v[134:135], off offset:64
	v_readlane_b32 s69, v254, 4
	v_readlane_b32 s70, v254, 5
	v_readlane_b32 s71, v254, 6
	v_cmp_lt_i32_e64 s[0:1], v24, v25
	v_readlane_b32 s72, v254, 7
	v_readlane_b32 s73, v254, 8
	v_readlane_b32 s74, v254, 9
	v_readlane_b32 s75, v254, 10
	v_readlane_b32 s76, v254, 11
	v_readlane_b32 s77, v254, 12
	v_readlane_b32 s78, v254, 13
	v_readlane_b32 s79, v254, 14
	v_readlane_b32 s80, v254, 15
	v_readlane_b32 s81, v254, 16
	v_readlane_b32 s82, v254, 17
	v_readlane_b32 s83, v254, 18
	s_waitcnt vmcnt(14)
	v_mfma_f32_16x16x32_bf16 v[56:59], v[4:7], v[28:31], 0
	s_waitcnt vmcnt(13)
	v_mfma_f32_16x16x32_bf16 v[68:71], v[4:7], v[32:35], 0
	s_waitcnt vmcnt(12)
	v_mfma_f32_16x16x32_bf16 v[76:79], v[4:7], v[36:39], 0
	s_waitcnt vmcnt(10)
	v_mfma_f32_16x16x32_bf16 v[4:7], v[4:7], v[44:47], 0
	v_mfma_f32_16x16x32_bf16 v[92:95], v[40:43], v[28:31], 0
	s_waitcnt vmcnt(7)
	v_mfma_f32_16x16x32_bf16 v[100:103], v[60:63], v[28:31], 0
	s_waitcnt vmcnt(4)
	v_mfma_f32_16x16x32_bf16 v[28:31], v[80:83], v[28:31], 0
	v_mfma_f32_16x16x32_bf16 v[108:111], v[40:43], v[32:35], 0
	v_mfma_f32_16x16x32_bf16 v[112:115], v[60:63], v[32:35], 0
	v_mfma_f32_16x16x32_bf16 v[32:35], v[80:83], v[32:35], 0
	v_mfma_f32_16x16x32_bf16 v[120:123], v[60:63], v[36:39], 0
	v_mfma_f32_16x16x32_bf16 v[60:63], v[60:63], v[44:47], 0
	v_mfma_f32_16x16x32_bf16 v[116:119], v[40:43], v[36:39], 0
	v_mfma_f32_16x16x32_bf16 v[36:39], v[80:83], v[36:39], 0
	v_mfma_f32_16x16x32_bf16 v[40:43], v[40:43], v[44:47], 0
	v_mfma_f32_16x16x32_bf16 v[44:47], v[80:83], v[44:47], 0
	v_mfma_f32_16x16x32_bf16 v[56:59], v[48:51], v[52:55], v[56:59]
	v_mfma_f32_16x16x32_bf16 v[68:71], v[48:51], v[64:67], v[68:71]
	s_waitcnt vmcnt(2)
	v_mfma_f32_16x16x32_bf16 v[80:83], v[88:91], v[52:55], v[92:95]
	s_waitcnt vmcnt(1)
	v_mfma_f32_16x16x32_bf16 v[92:95], v[96:99], v[52:55], v[100:103]
	s_waitcnt vmcnt(0)
	v_mfma_f32_16x16x32_bf16 v[28:31], v[104:107], v[52:55], v[28:31]
	v_mfma_f32_16x16x32_bf16 v[52:55], v[88:91], v[64:67], v[108:111]
	v_mfma_f32_16x16x32_bf16 v[100:103], v[96:99], v[64:67], v[112:115]
	v_mfma_f32_16x16x32_bf16 v[32:35], v[104:107], v[64:67], v[32:35]
	v_mfma_f32_16x16x32_bf16 v[64:67], v[48:51], v[72:75], v[76:79]
	v_mfma_f32_16x16x32_bf16 v[4:7], v[48:51], v[84:87], v[4:7]
	v_mfma_f32_16x16x32_bf16 v[48:51], v[96:99], v[84:87], v[60:63]
	s_nop 2
	global_load_dwordx4 v[60:63], v[124:125], off offset:128
	v_mfma_f32_16x16x32_bf16 v[76:79], v[88:91], v[72:75], v[116:119]
	v_mfma_f32_16x16x32_bf16 v[108:111], v[96:99], v[72:75], v[120:123]
	v_mfma_f32_16x16x32_bf16 v[36:39], v[104:107], v[72:75], v[36:39]
	v_mfma_f32_16x16x32_bf16 v[40:43], v[88:91], v[84:87], v[40:43]
	v_mfma_f32_16x16x32_bf16 v[44:47], v[104:107], v[84:87], v[44:47]
	global_load_dwordx4 v[72:75], v[8:9], off offset:128
	global_load_dwordx4 v[84:87], v[8:9], off offset:192
	global_load_dwordx4 v[88:91], v[124:125], off offset:192
	global_load_dwordx4 v[96:99], v[126:127], off offset:128
	global_load_dwordx4 v[104:107], v[126:127], off offset:192
	global_load_dwordx4 v[112:115], v[130:131], off offset:128
	global_load_dwordx4 v[116:119], v[130:131], off offset:192
	global_load_dwordx4 v[120:123], v[134:135], off offset:128
	s_nop 0
	global_load_dwordx4 v[124:127], v[134:135], off offset:192
	s_waitcnt vmcnt(8)
	v_mfma_f32_16x16x32_bf16 v[56:59], v[60:63], v[72:75], v[56:59]
	s_waitcnt vmcnt(5)
	v_mfma_f32_16x16x32_bf16 v[80:83], v[96:99], v[72:75], v[80:83]
	s_waitcnt vmcnt(3)
	v_mfma_f32_16x16x32_bf16 v[92:95], v[112:115], v[72:75], v[92:95]
	s_waitcnt vmcnt(1)
	v_mfma_f32_16x16x32_bf16 v[28:31], v[120:123], v[72:75], v[28:31]
	global_load_dwordx4 v[72:75], v[128:129], off offset:128
	s_nop 0
	global_load_dwordx4 v[128:131], v[128:129], off offset:192
	s_waitcnt vmcnt(1)
	v_mfma_f32_16x16x32_bf16 v[68:71], v[60:63], v[72:75], v[68:71]
	v_mfma_f32_16x16x32_bf16 v[52:55], v[96:99], v[72:75], v[52:55]
	v_mfma_f32_16x16x32_bf16 v[100:103], v[112:115], v[72:75], v[100:103]
	v_mfma_f32_16x16x32_bf16 v[32:35], v[120:123], v[72:75], v[32:35]
	global_load_dwordx4 v[72:75], v[132:133], off offset:128
	s_nop 0
	global_load_dwordx4 v[132:135], v[132:133], off offset:192
	s_nop 0
	global_load_dwordx4 v[136:139], v[140:141], off offset:128
	s_waitcnt vmcnt(2)
	v_mfma_f32_16x16x32_bf16 v[64:67], v[60:63], v[72:75], v[64:67]
	v_mfma_f32_16x16x32_bf16 v[76:79], v[96:99], v[72:75], v[76:79]
	v_mfma_f32_16x16x32_bf16 v[108:111], v[112:115], v[72:75], v[108:111]
	v_mfma_f32_16x16x32_bf16 v[36:39], v[120:123], v[72:75], v[36:39]
	global_load_dwordx4 v[72:75], v[140:141], off offset:192
	s_barrier
; #define LAS __attribute__((address_space(3)))
;     __device__ __forceinline__ void small(size_t row, int col, const f32x4 v0, const f32x4 v1) const { *(u32x4*)(Ub + row * DSSM + col) = pack8(v0, v1); }
; template <class Epi, bool PAIR>
; __device__ __forceinline__ void small_gemm(LAS unsigned char* lds, const bf16_t* A, int lda, const bf16_t* B, int ldb, int K, int nrg, int nct, size_t row_base, int col_base, const Epi& E, int G, int c) {
;     ...
;             for (int mi = 0; mi < 4; ++mi) a[mi] = *(const bf16x8*)(ap + (size_t)(mi * 16) * lda + ks * 32);
; #pragma unroll
;             for (int ni = 0; ni < 4; ++ni) { const int roff = PAIR ? ((ni & 1) * 16 + (ni >> 1) * 128) : ni * 16; b[ni] = *(const bf16x8*)(bp + (size_t)roff * ldb + ks * 32); }
; #pragma unroll
;             for (int mi = 0; mi < 4; ++mi)
; #pragma unroll
;                 for (int ni = 0; ni < 4; ++ni) acc[mi][ni] = __builtin_amdgcn_mfma_f32_16x16x32_bf16(b[ni], a[mi], acc[mi][ni], 0, 0, 0);
;         }
;         __syncthreads();
; #pragma unroll
;         for (int mi = 0; mi < 4; ++mi)
; #pragma unroll
;             for (int ni = 0; ni < 4; ++ni) *(LAS f32x4*)(red + (wid * 64 + mi * 16 + fr) * 68 + ni * 16 + 4 * fq) = acc[mi][ni];
;         __syncthreads();
;         if constexpr (!PAIR) {
;             const int r = tid >> 3, pc = tid & 7; f32x4 v0 = (f32x4){0.f, 0.f, 0.f, 0.f}, v1 = v0;
; #pragma unroll
;             for (int w = 0; w < 8; ++w) { v0 += *(const LAS f32x4*)(red + (w * 64 + r) * 68 + pc * 8); v1 += *(const LAS f32x4*)(red + (w * 64 + r) * 68 + pc * 8 + 4); }
;             E.small(row_base + rg * 64 + r, col_base + ct * 64 + pc * 8, v0, v1);
	s_waitcnt vmcnt(1)
	v_mfma_f32_16x16x32_bf16 v[4:7], v[60:63], v[136:139], v[4:7]
	v_mfma_f32_16x16x32_bf16 v[40:43], v[96:99], v[136:139], v[40:43]
	v_mfma_f32_16x16x32_bf16 v[56:59], v[88:91], v[84:87], v[56:59]
	v_mfma_f32_16x16x32_bf16 v[28:31], v[124:127], v[84:87], v[28:31]
	v_mfma_f32_16x16x32_bf16 v[48:51], v[112:115], v[136:139], v[48:51]
	v_mfma_f32_16x16x32_bf16 v[60:63], v[104:107], v[84:87], v[80:83]
	v_mfma_f32_16x16x32_bf16 v[80:83], v[116:119], v[84:87], v[92:95]
	s_nop 3
	ds_write_b128 v22, v[56:59]
	s_nop 1
	ds_write_b128 v22, v[60:63] offset:64
	ds_write_b128 v22, v[80:83] offset:128
	v_add_u32_e32 v56, s11, v11
	v_mfma_f32_16x16x32_bf16 v[68:71], v[88:91], v[128:131], v[68:71]
	v_ashrrev_i32_e32 v57, 31, v56
	v_mfma_f32_16x16x32_bf16 v[84:87], v[116:119], v[128:131], v[100:103]
	v_mfma_f32_16x16x32_bf16 v[52:55], v[104:107], v[128:131], v[52:55]
	ds_write_b128 v22, v[28:31] offset:192
	s_nop 3
	ds_write_b128 v22, v[68:71] offset:4352
	s_nop 1
	ds_write_b128 v22, v[52:55] offset:4416
	v_or_b32_e32 v68, s9, v12
	v_mfma_f32_16x16x32_bf16 v[32:35], v[124:127], v[128:131], v[32:35]
	v_ashrrev_i32_e32 v69, 31, v68
	v_mfma_f32_16x16x32_bf16 v[44:47], v[120:123], v[136:139], v[44:47]
	v_mfma_f32_16x16x32_bf16 v[64:67], v[88:91], v[132:135], v[64:67]
	ds_write_b128 v22, v[84:87] offset:4480
	s_nop 3
	ds_write_b128 v22, v[32:35] offset:4544
	s_nop 1
	ds_write_b128 v22, v[64:67] offset:8704
	v_mfma_f32_16x16x32_bf16 v[76:79], v[104:107], v[132:135], v[76:79]
	s_waitcnt vmcnt(0)
	v_mfma_f32_16x16x32_bf16 v[4:7], v[88:91], v[72:75], v[4:7]
	v_lshlrev_b64 v[90:91], 11, v[56:57]
	v_mfma_f32_16x16x32_bf16 v[92:95], v[116:119], v[132:135], v[108:111]
	v_mfma_f32_16x16x32_bf16 v[28:31], v[104:107], v[72:75], v[40:43]
	v_mfma_f32_16x16x32_bf16 v[36:39], v[124:127], v[132:135], v[36:39]
	s_nop 1
	ds_write_b128 v22, v[76:79] offset:8768
	s_nop 2
	ds_write_b128 v22, v[92:95] offset:8832
	s_nop 0
	ds_write_b128 v22, v[36:39] offset:8896
	v_lshlrev_b64 v[92:93], 1, v[68:69]
	v_mfma_f32_16x16x32_bf16 v[32:35], v[116:119], v[72:75], v[48:51]
	ds_write_b128 v22, v[4:7] offset:13056
	ds_write_b128 v22, v[28:31] offset:13120
	s_nop 5
	ds_write_b128 v22, v[32:35] offset:13184
	v_lshlrev_b64 v[76:77], 2, v[68:69]
	v_mfma_f32_16x16x32_bf16 v[4:7], v[124:127], v[72:75], v[44:47]
	v_lshl_add_u64 v[72:73], s[68:69], 0, v[76:77]
	v_lshl_add_u64 v[80:81], s[70:71], 0, v[76:77]
	s_nop 5
	ds_write_b128 v22, v[4:7] offset:13248
	v_lshlrev_b64 v[4:5], 7, v[56:57]
	v_lshl_add_u64 v[52:53], s[14:15], 0, v[4:5]
	s_waitcnt lgkmcnt(0)
	s_barrier
	global_load_dwordx4 v[6:9], v[52:53], off
	global_load_dwordx4 v[28:31], v[52:53], off offset:16
	global_load_dwordx4 v[32:35], v[52:53], off offset:32
	global_load_dwordx4 v[36:39], v[52:53], off offset:48
	global_load_dwordx4 v[40:43], v[52:53], off offset:64
	global_load_dwordx4 v[44:47], v[52:53], off offset:80
	global_load_dwordx4 v[48:51], v[52:53], off offset:96
	s_nop 0
	global_load_dwordx4 v[52:55], v[52:53], off offset:112
	v_lshl_add_u64 v[56:57], s[60:61], 0, v[90:91]
	v_lshl_add_u64 v[56:57], v[56:57], 0, v[92:93]
	global_load_dwordx4 v[56:59], v[56:57], off
	ds_read_b128 v[60:63], v13
	ds_read_b128 v[64:67], v13 offset:16
	s_waitcnt lgkmcnt(1)
	v_pk_add_f32 v[88:89], v[62:63], 0 op_sel_hi:[1,0]
	v_pk_add_f32 v[94:95], v[60:61], 0 op_sel_hi:[1,0]
	ds_read_b128 v[60:63], v13 offset:17408
	global_load_dwordx4 v[68:71], v[72:73], off offset:16
	s_nop 0
	global_load_dwordx4 v[72:75], v[72:73], off
	s_nop 0
	global_load_dwordx4 v[76:79], v[80:81], off offset:16
	s_nop 0
	global_load_dwordx4 v[80:83], v[80:81], off
	ds_read_b128 v[84:87], v13 offset:17424
	s_waitcnt lgkmcnt(2)
	v_pk_add_f32 v[96:97], v[64:65], 0 op_sel_hi:[1,0]
	s_waitcnt lgkmcnt(1)
	v_pk_add_f32 v[98:99], v[88:89], v[62:63]
	ds_read_b128 v[62:65], v13 offset:34816
	v_pk_add_f32 v[66:67], v[66:67], 0 op_sel_hi:[1,0]
	v_pk_add_f32 v[60:61], v[94:95], v[60:61]
	s_waitcnt lgkmcnt(1)
	v_pk_add_f32 v[94:95], v[66:67], v[86:87]
	ds_read_b128 v[86:89], v13 offset:34832
	v_pk_add_f32 v[84:85], v[96:97], v[84:85]
	s_waitcnt lgkmcnt(1)
	v_pk_add_f32 v[96:97], v[98:99], v[64:65]
	ds_read_b128 v[64:67], v13 offset:52224
	v_pk_add_f32 v[98:99], v[60:61], v[62:63]
	ds_read_b128 v[60:63], v13 offset:52240
	s_waitcnt lgkmcnt(2)
	v_pk_add_f32 v[88:89], v[94:95], v[88:89]
	v_pk_add_f32 v[94:95], v[84:85], v[86:87]
	s_waitcnt lgkmcnt(1)
	v_pk_add_f32 v[66:67], v[96:97], v[66:67]
	ds_read_b128 v[84:87], v14
	v_pk_add_f32 v[96:97], v[98:99], v[64:65]
	s_waitcnt lgkmcnt(1)
	v_pk_add_f32 v[98:99], v[88:89], v[62:63]
	ds_read_b128 v[62:65], v15
	v_pk_add_f32 v[60:61], v[94:95], v[60:61]
	s_waitcnt lgkmcnt(1)
	v_pk_add_f32 v[94:95], v[66:67], v[86:87]
	ds_read_b128 v[86:89], v16
	v_pk_add_f32 v[84:85], v[96:97], v[84:85]
	s_waitcnt lgkmcnt(1)
;     __device__ __forceinline__ void piece(size_t row, int col, f32x4 v0, f32x4 v1, const f32x4 a0, const f32x4 a1, const f32x4 b0, const f32x4 b1, const f32x4 c0, const f32x4 c1,
;                                           float mean, float rstd, float& s, float& ss) const {
;     ...
;         if constexpr (RECOMP) { f32x4 r0, r1; unpack8(*(const u32x4*)(Tin + row * DM + col), r0, r1);
;             r0 = (r0 - mean) * rstd * a0 + b0; r1 = (r1 - mean) * rstd * a1 + b1; v0 = r0 * ALPHA + v0; v1 = r1 * ALPHA + v1;
;             if constexpr (MODE == 5) { v0 = v0 + c0; v1 = v1 + c1; } }
;         if constexpr (MODE == 4) { v0 = (v0 - a0 * mean) * rstd + b0; v1 = (v1 - a1 * mean) * rstd + b1;
; #pragma unroll
;             for (int e = 0; e < 4; ++e) { const float x = fmaxf(v0[e], 0.f), y = fmaxf(v1[e], 0.f); v0[e] = x * x; v1[e] = y * y; } }
;         if constexpr (PROD) {
; #pragma unroll
;             for (int e = 0; e < 4; ++e) { s += v0[e] + v1[e]; ss += v0[e] * v0[e] + v1[e] * v1[e]; } }
;         if constexpr (MODE == 5) { float* o = (float*)O + row * ldo + col; *(f32x4*)o = v0; *(f32x4*)(o + 4) = v1; }
;         else *(u32x4*)((bf16_t*)O + row * ldo + col) = pack8(v0, v1);
;     __device__ __forceinline__ void small(size_t row, int col, const f32x4 v0, const f32x4 v1) const {
;         const f32x4 z = (f32x4){0.f, 0.f, 0.f, 0.f};
;         float mean = 0.f, rstd = 0.f;
;         if constexpr (CONS) { float s0, q0, s1, q1; stats_of(st_in, row, 0, s0, q0); stats_of(st_in, row, 1, s1, q1); mean = (s0 + s1) * (1.f / DM); rstd = __builtin_amdgcn_rsqf(fmaxf((q0 + q1) * (1.f / DM) - mean * mean, 0.f) + LN_EPS); }
;         float s = 0.f, ss = 0.f;
;         piece(row, col, v0, v1, CONS ? *(const f32x4*)(va + col) : z, CONS ? *(const f32x4*)(va + col + 4) : z, CONS ? *(const f32x4*)(vb + col) : z, CONS ? *(const f32x4*)(vb + col + 4) : z,
;               (MODE == 5) ? *(const f32x4*)(bias + col) : z, (MODE == 5) ? *(const f32x4*)(bias + col + 4) : z, mean, rstd, s, ss);
;         if constexpr (PROD) { s += __shfl_xor(s, 1); ss += __shfl_xor(ss, 1); s += __shfl_xor(s, 2); ss += __shfl_xor(ss, 2); s += __shfl_xor(s, 4); ss += __shfl_xor(ss, 4);
;             if ((threadIdx.x & 7) == 0) st_out[row * 16 + (col >> 6)] = (f32x2){s, ss}; }
	v_pk_add_f32 v[96:97], v[98:99], v[64:65]
	ds_read_b128 v[64:67], v17
	v_pk_add_f32 v[98:99], v[60:61], v[62:63]
	ds_read_b128 v[60:63], v18
	s_waitcnt lgkmcnt(2)
	v_pk_add_f32 v[88:89], v[94:95], v[88:89]
	v_pk_add_f32 v[94:95], v[84:85], v[86:87]
	s_waitcnt lgkmcnt(1)
	v_pk_add_f32 v[96:97], v[96:97], v[66:67]
	v_pk_add_f32 v[98:99], v[98:99], v[64:65]
	ds_read_b128 v[64:67], v19
	ds_read_b128 v[84:87], v20
	s_waitcnt lgkmcnt(2)
	v_pk_add_f32 v[88:89], v[88:89], v[62:63]
	v_pk_add_f32 v[94:95], v[94:95], v[60:61]
	ds_read_b128 v[60:63], v21
	s_waitcnt lgkmcnt(2)
	v_pk_add_f32 v[66:67], v[96:97], v[66:67]
	v_pk_add_f32 v[64:65], v[98:99], v[64:65]
	s_waitcnt lgkmcnt(1)
	v_pk_add_f32 v[84:85], v[94:95], v[84:85]
	v_pk_add_f32 v[86:87], v[88:89], v[86:87]
	s_waitcnt lgkmcnt(0)
	v_pk_add_f32 v[62:63], v[66:67], v[62:63]
	v_pk_add_f32 v[60:61], v[64:65], v[60:61]
	s_waitcnt vmcnt(12)
	v_pk_add_f32 v[6:7], v[6:7], v[8:9]
	s_nop 0
	v_pk_add_f32 v[6:7], v[6:7], 0 op_sel_hi:[1,0]
	s_waitcnt vmcnt(11)
	v_pk_add_f32 v[8:9], v[28:29], v[30:31]
	s_waitcnt vmcnt(7)
	v_pk_add_f32 v[28:29], v[44:45], v[46:47]
	v_pk_add_f32 v[6:7], v[6:7], v[8:9]
	v_pk_add_f32 v[8:9], v[32:33], v[34:35]
	s_waitcnt vmcnt(4)
	v_lshlrev_b32_e32 v30, 16, v57
	v_pk_add_f32 v[6:7], v[6:7], v[8:9]
	v_pk_add_f32 v[8:9], v[36:37], v[38:39]
	v_and_b32_e32 v31, 0xffff0000, v57
	v_pk_add_f32 v[6:7], v[6:7], v[8:9]
	v_pk_add_f32 v[8:9], v[40:41], v[42:43]
	v_lshlrev_b32_e32 v32, 16, v58
	v_pk_add_f32 v[8:9], v[8:9], 0 op_sel_hi:[1,0]
	v_and_b32_e32 v33, 0xffff0000, v58
	v_pk_add_f32 v[8:9], v[8:9], v[28:29]
	v_pk_add_f32 v[28:29], v[48:49], v[50:51]
	v_lshlrev_b32_e32 v34, 16, v59
	v_pk_add_f32 v[8:9], v[8:9], v[28:29]
	v_pk_add_f32 v[28:29], v[52:53], v[54:55]
	v_and_b32_e32 v35, 0xffff0000, v59
	v_pk_add_f32 v[8:9], v[8:9], v[28:29]
	s_nop 0
	v_pk_add_f32 v[6:7], v[6:7], v[8:9]
	v_and_b32_e32 v9, 0xffff0000, v56
	v_pk_mul_f32 v[6:7], v[6:7], s[8:9] op_sel_hi:[1,0]
	s_nop 0
	v_fma_f32 v7, -v6, v6, v7
	v_max_f32_e32 v7, 0, v7
	v_add_f32_e32 v7, 0x3727c5ac, v7
	v_rsq_f32_e32 v8, v7
	v_lshlrev_b32_e32 v7, 16, v56
	v_sub_f32_e32 v29, v9, v6
	v_sub_f32_e32 v28, v7, v6
	v_sub_f32_e32 v31, v31, v6
	v_sub_f32_e32 v30, v30, v6
	v_pk_mul_f32 v[28:29], v[8:9], v[28:29] op_sel_hi:[0,1]
	v_sub_f32_e32 v33, v33, v6
	v_sub_f32_e32 v32, v32, v6
	v_sub_f32_e32 v7, v35, v6
	v_sub_f32_e32 v6, v34, v6
	v_pk_mul_f32 v[30:31], v[8:9], v[30:31] op_sel_hi:[0,1]
	s_waitcnt vmcnt(0)
	v_pk_fma_f32 v[28:29], v[72:73], v[28:29], v[80:81]
	v_pk_mul_f32 v[6:7], v[8:9], v[6:7] op_sel_hi:[0,1]
	v_pk_mul_f32 v[8:9], v[8:9], v[32:33] op_sel_hi:[0,1]
	v_pk_fma_f32 v[8:9], v[68:69], v[8:9], v[76:77]
	v_pk_fma_f32 v[6:7], v[70:71], v[6:7], v[78:79]
	v_pk_fma_f32 v[28:29], v[28:29], s[10:11], v[84:85] op_sel_hi:[1,0,1]
	v_pk_fma_f32 v[32:33], v[6:7], s[10:11], v[62:63] op_sel_hi:[1,0,1]
	v_pk_fma_f32 v[6:7], v[8:9], s[10:11], v[60:61] op_sel_hi:[1,0,1]
	v_pk_mul_f32 v[34:35], v[28:29], v[28:29]
	v_pk_fma_f32 v[30:31], v[74:75], v[30:31], v[82:83]
	v_pk_fma_f32 v[34:35], v[6:7], v[6:7], v[34:35]
	v_pk_fma_f32 v[30:31], v[30:31], s[10:11], v[86:87] op_sel_hi:[1,0,1]
	v_pk_add_f32 v[34:35], v[34:35], v[34:35] op_sel_hi:[1,0]
	v_mov_b32_e32 v36, v30
	v_mov_b32_e32 v37, v32
	v_mul_f32_e32 v34, v30, v30
	v_pk_fma_f32 v[36:37], v[36:37], v[36:37], v[34:35] op_sel_hi:[1,1,0]
	v_cndmask_b32_e64 v34, v23, v24, s[0:1]
	v_pk_add_f32 v[8:9], v[28:29], v[6:7]
	v_lshlrev_b32_e32 v40, 2, v34
	v_mov_b32_e32 v36, v31
	v_mov_b32_e32 v34, v33
	v_add_f32_e32 v8, 0, v8
	v_pk_add_f32 v[34:35], v[36:37], v[34:35]
	v_pk_add_f32 v[36:37], v[30:31], v[32:33]
	v_pk_mul_f32 v[38:39], v[30:31], v[30:31]
	v_add_f32_e32 v8, v9, v8
	v_mul_f32_e32 v9, v33, v33
	v_mov_b32_e32 v37, v39
	v_pk_add_f32 v[8:9], v[36:37], v[8:9]
	v_cmp_lt_i32_e64 s[0:1], v26, v25
	v_pk_add_f32 v[8:9], v[8:9], v[34:35]
	ds_bpermute_b32 v34, v40, v8
	ds_bpermute_b32 v35, v40, v9
	v_cndmask_b32_e64 v36, v23, v26, s[0:1]
	v_lshlrev_b32_e32 v36, 2, v36
	v_cmp_lt_i32_e64 s[0:1], v27, v25
	v_cvt_pk_bf16_f32 v28, v28, v29
	s_waitcnt lgkmcnt(0)
	v_pk_add_f32 v[8:9], v[8:9], v[34:35]
	ds_bpermute_b32 v34, v36, v8
	ds_bpermute_b32 v35, v36, v9
	v_cvt_pk_bf16_f32 v29, v30, v31
	v_cvt_pk_bf16_f32 v30, v6, v7
	v_cvt_pk_bf16_f32 v31, v32, v33
	v_lshl_add_u64 v[32:33], s[88:89], 0, v[90:91]
	s_waitcnt lgkmcnt(0)
	v_pk_add_f32 v[6:7], v[8:9], v[34:35]
	v_cndmask_b32_e64 v8, v23, v27, s[0:1]
	v_lshlrev_b32_e32 v9, 2, v8
	ds_bpermute_b32 v8, v9, v6
	ds_bpermute_b32 v9, v9, v7
	v_lshl_add_u64 v[32:33], v[32:33], 0, v[92:93]
	global_store_dwordx4 v[32:33], v[28:31], off sc0 sc1
	s_and_saveexec_b64 s[0:1], vcc
	s_cbranch_execz .LBB0_1282
	v_lshl_add_u64 v[4:5], s[90:91], 0, v[4:5]
	s_ashr_i32 s21, s20, 31
	v_lshl_add_u64 v[4:5], s[20:21], 3, v[4:5]
	s_waitcnt lgkmcnt(0)
	v_pk_add_f32 v[6:7], v[6:7], v[8:9]
	global_store_dwordx2 v[4:5], v[6:7], off sc0 sc1
	s_branch .LBB0_1282

; __device__ __forceinline__ unsigned xb_add(unsigned* p, unsigned v) { return __hip_atomic_fetch_add(p, v, __ATOMIC_RELAXED, __HIP_MEMORY_SCOPE_AGENT); }
; __device__ __forceinline__ void xcd_barrier(const XcdBarrier& b) {
;     ...
;         const unsigned old = xb_add(&bar[XB_XSUB(b.x)], 1u);
;         const unsigned gen = old / nloc;
;         if (old + 1u == (gen + 1u) * nloc) {
;             __builtin_amdgcn_fence(__ATOMIC_RELEASE, "agent");
;             asm volatile("s_waitcnt vmcnt(0)" ::: "memory");
;             const unsigned og = xb_add(&bar[XB_TOP], 1u);
;             const unsigned tg = og / nx;
;             if (og + 1u == (tg + 1u) * nx) xb_add(&bar[XB_TOPGEN], 1u);
.Lnowb_8:
	s_waitcnt lgkmcnt(0)
	s_waitcnt vmcnt(0)
	v_mbcnt_lo_u32_b32 v1, s10, 0
	v_mbcnt_hi_u32_b32 v1, s11, v1
	v_cmp_eq_u32_e32 vcc, 0, v1
	s_and_saveexec_b64 s[12:13], vcc
	s_cbranch_execz .LBB0_1320
	s_bcnt1_i32_b64 s3, s[10:11]
	v_mov_b32_e32 v2, 0x3000
	v_mov_b32_e32 v3, s3
	global_atomic_add v2, v2, v3, s[58:59] offset:1024 sc0

; template <class Epi, bool PAIR>
; __device__ __forceinline__ void small_gemm(LAS unsigned char* lds, const bf16_t* A, int lda, const bf16_t* B, int ldb, int K, int nrg, int nct, size_t row_base, int col_base, const Epi& E, int G, int c) {
;     ...
;         const bf16_t* ap = A + (size_t)(rg * 64 + fr) * lda + k0 + fq * 8;
;         const bf16_t* bp;
;         if (PAIR) { const int ch0 = 32 * ct; bp = B + (size_t)(DSSM + 256 * (ch0 >> 7) + (ch0 & 127) + fr) * ldb + k0 + fq * 8; }
;         else bp = B + (size_t)(ct * 64 + fr) * ldb + k0 + fq * 8;
; #pragma unroll 4
;         for (int ks = 0; ks < nks; ++ks) {
;             bf16x8 a[4], b[4];
; #pragma unroll
;             for (int mi = 0; mi < 4; ++mi) a[mi] = *(const bf16x8*)(ap + (size_t)(mi * 16) * lda + ks * 32);
; #pragma unroll
;             for (int ni = 0; ni < 4; ++ni) { const int roff = PAIR ? ((ni & 1) * 16 + (ni >> 1) * 128) : ni * 16; b[ni] = *(const bf16x8*)(bp + (size_t)roff * ldb + ks * 32); }
; #pragma unroll
;             for (int mi = 0; mi < 4; ++mi)
; #pragma unroll
;                 for (int ni = 0; ni < 4; ++ni) acc[mi][ni] = __builtin_amdgcn_mfma_f32_16x16x32_bf16(b[ni], a[mi], acc[mi][ni], 0, 0, 0);
;         }
.LBB0_1387:
	s_ashr_i32 s11, s7, 31
	s_lshr_b32 s11, s11, 30
	s_add_i32 s11, s7, s11
	s_ashr_i32 s11, s11, 2
	s_lshl_b32 s12, s11, 6
	v_or_b32_e32 v0, s12, v48
	v_ashrrev_i32_e32 v1, 31, v0
	v_lshlrev_b64 v[0:1], 11, v[0:1]
	v_lshl_add_u64 v[118:119], v[46:47], 0, v[0:1]
	s_lshl_b32 s13, s11, 8
	v_add_co_u32_e32 v142, vcc, s3, v118
	s_sub_i32 s11, s4, s13
	s_nop 0
	v_addc_co_u32_e32 v143, vcc, 0, v119, vcc
	v_add_u32_e32 v2, s11, v48
	v_add_co_u32_e32 v144, vcc, s5, v118
	v_ashrrev_i32_e32 v3, 31, v2
	s_nop 0
	v_addc_co_u32_e32 v145, vcc, 0, v119, vcc
	v_lshlrev_b64 v[2:3], 11, v[2:3]
	v_add_co_u32_e32 v146, vcc, s6, v118
	v_lshl_add_u64 v[122:123], v[44:45], 0, v[2:3]
	s_nop 0
	v_addc_co_u32_e32 v147, vcc, 0, v119, vcc
	v_add_co_u32_e32 v126, vcc, s3, v122
	global_load_dwordx4 v[0:3], v[118:119], off
	s_nop 0
	v_addc_co_u32_e32 v127, vcc, 0, v123, vcc
	v_add_co_u32_e32 v134, vcc, s5, v122
	global_load_dwordx4 v[4:7], v[118:119], off offset:64
	global_load_dwordx4 v[8:11], v[122:123], off
	v_addc_co_u32_e32 v135, vcc, 0, v123, vcc
	v_add_co_u32_e32 v138, vcc, s6, v122
	global_load_dwordx4 v[12:15], v[142:143], off
	global_load_dwordx4 v[16:19], v[144:145], off
	global_load_dwordx4 v[20:23], v[146:147], off
	global_load_dwordx4 v[24:27], v[122:123], off offset:64
	v_addc_co_u32_e32 v139, vcc, 0, v123, vcc
	global_load_dwordx4 v[32:35], v[126:127], off
	global_load_dwordx4 v[36:39], v[126:127], off offset:64
	global_load_dwordx4 v[62:65], v[134:135], off
	global_load_dwordx4 v[66:69], v[134:135], off offset:64
	global_load_dwordx4 v[74:77], v[138:139], off
	global_load_dwordx4 v[78:81], v[138:139], off offset:64
	global_load_dwordx4 v[82:85], v[142:143], off offset:64
	global_load_dwordx4 v[90:93], v[144:145], off offset:64
	global_load_dwordx4 v[98:101], v[146:147], off offset:64
	s_add_i32 s7, s7, s92
	s_add_i32 s4, s4, s48
	s_cmpk_lt_i32 s7, 0x100
	s_waitcnt vmcnt(12)
	v_mfma_f32_16x16x32_bf16 v[86:89], v[12:15], v[8:11], 0
	v_mfma_f32_16x16x32_bf16 v[28:31], v[0:3], v[8:11], 0
	s_waitcnt vmcnt(8)
	v_mfma_f32_16x16x32_bf16 v[40:43], v[0:3], v[32:35], 0
	s_waitcnt vmcnt(6)
	v_mfma_f32_16x16x32_bf16 v[70:73], v[0:3], v[62:65], 0
	v_mfma_f32_16x16x32_bf16 v[94:97], v[16:19], v[8:11], 0
	v_mfma_f32_16x16x32_bf16 v[8:11], v[20:23], v[8:11], 0
	v_mfma_f32_16x16x32_bf16 v[102:105], v[12:15], v[32:35], 0
	v_mfma_f32_16x16x32_bf16 v[106:109], v[16:19], v[32:35], 0
	v_mfma_f32_16x16x32_bf16 v[32:35], v[20:23], v[32:35], 0
	v_mfma_f32_16x16x32_bf16 v[110:113], v[12:15], v[62:65], 0
	v_mfma_f32_16x16x32_bf16 v[114:117], v[16:19], v[62:65], 0
	v_mfma_f32_16x16x32_bf16 v[62:65], v[20:23], v[62:65], 0
	s_waitcnt vmcnt(4)
	v_mfma_f32_16x16x32_bf16 v[12:15], v[12:15], v[74:77], 0
	v_mfma_f32_16x16x32_bf16 v[0:3], v[0:3], v[74:77], 0
	v_mfma_f32_16x16x32_bf16 v[16:19], v[16:19], v[74:77], 0
	v_mfma_f32_16x16x32_bf16 v[20:23], v[20:23], v[74:77], 0
	v_mfma_f32_16x16x32_bf16 v[28:31], v[4:7], v[24:27], v[28:31]
	v_mfma_f32_16x16x32_bf16 v[40:43], v[4:7], v[36:39], v[40:43]
	v_mfma_f32_16x16x32_bf16 v[70:73], v[4:7], v[66:69], v[70:73]
	s_waitcnt vmcnt(2)
	v_mfma_f32_16x16x32_bf16 v[74:77], v[82:85], v[24:27], v[86:89]
	s_waitcnt vmcnt(1)
	v_mfma_f32_16x16x32_bf16 v[86:89], v[90:93], v[24:27], v[94:97]
	s_waitcnt vmcnt(0)
	v_mfma_f32_16x16x32_bf16 v[24:27], v[98:101], v[24:27], v[8:11]
	v_mfma_f32_16x16x32_bf16 v[94:97], v[82:85], v[36:39], v[102:105]
	v_mfma_f32_16x16x32_bf16 v[102:105], v[90:93], v[36:39], v[106:109]
	v_mfma_f32_16x16x32_bf16 v[32:35], v[98:101], v[36:39], v[32:35]
	v_mfma_f32_16x16x32_bf16 v[36:39], v[82:85], v[66:69], v[110:113]
	v_mfma_f32_16x16x32_bf16 v[106:109], v[90:93], v[66:69], v[114:117]
	v_mfma_f32_16x16x32_bf16 v[62:65], v[98:101], v[66:69], v[62:65]
	v_mfma_f32_16x16x32_bf16 v[66:69], v[82:85], v[78:81], v[12:15]
	global_load_dwordx4 v[8:11], v[118:119], off offset:128
	global_load_dwordx4 v[82:85], v[118:119], off offset:192
	global_load_dwordx4 v[110:113], v[122:123], off offset:128
	global_load_dwordx4 v[114:117], v[142:143], off offset:128
	v_mfma_f32_16x16x32_bf16 v[4:7], v[4:7], v[78:81], v[0:3]
	v_mfma_f32_16x16x32_bf16 v[90:93], v[90:93], v[78:81], v[16:19]
	v_mfma_f32_16x16x32_bf16 v[20:23], v[98:101], v[78:81], v[20:23]
	global_load_dwordx4 v[78:81], v[144:145], off offset:128
	global_load_dwordx4 v[98:101], v[146:147], off offset:128
	global_load_dwordx4 v[118:121], v[122:123], off offset:192
	s_waitcnt vmcnt(4)
	v_mfma_f32_16x16x32_bf16 v[122:125], v[8:11], v[110:113], v[28:31]
	s_nop 2
	global_load_dwordx4 v[28:31], v[126:127], off offset:128
	s_nop 0
	global_load_dwordx4 v[126:129], v[126:127], off offset:192
	s_nop 0
	global_load_dwordx4 v[130:133], v[134:135], off offset:128
	global_load_dwordx4 v[12:15], v[134:135], off offset:192
	s_nop 0
	global_load_dwordx4 v[134:137], v[138:139], off offset:128
	global_load_dwordx4 v[0:3], v[138:139], off offset:192
	s_waitcnt vmcnt(5)
	v_mfma_f32_16x16x32_bf16 v[40:43], v[8:11], v[28:31], v[40:43]
	global_load_dwordx4 v[16:19], v[142:143], off offset:192
	s_waitcnt vmcnt(4)
	v_mfma_f32_16x16x32_bf16 v[70:73], v[8:11], v[130:133], v[70:73]
	s_waitcnt vmcnt(2)
	v_mfma_f32_16x16x32_bf16 v[138:141], v[8:11], v[134:137], v[4:7]
	global_load_dwordx4 v[8:11], v[144:145], off offset:192
	s_nop 1
	global_load_dwordx4 v[4:7], v[146:147], off offset:192
	v_mfma_f32_16x16x32_bf16 v[74:77], v[114:117], v[110:113], v[74:77]
	s_barrier
; #define LAS __attribute__((address_space(3)))
; template <class Epi, bool PAIR>
; __device__ __forceinline__ void small_gemm(LAS unsigned char* lds, const bf16_t* A, int lda, const bf16_t* B, int ldb, int K, int nrg, int nct, size_t row_base, int col_base, const Epi& E, int G, int c) {
;     ...
;             for (int mi = 0; mi < 4; ++mi) a[mi] = *(const bf16x8*)(ap + (size_t)(mi * 16) * lda + ks * 32);
; #pragma unroll
;             for (int ni = 0; ni < 4; ++ni) { const int roff = PAIR ? ((ni & 1) * 16 + (ni >> 1) * 128) : ni * 16; b[ni] = *(const bf16x8*)(bp + (size_t)roff * ldb + ks * 32); }
; #pragma unroll
;             for (int mi = 0; mi < 4; ++mi)
; #pragma unroll
;                 for (int ni = 0; ni < 4; ++ni) acc[mi][ni] = __builtin_amdgcn_mfma_f32_16x16x32_bf16(b[ni], a[mi], acc[mi][ni], 0, 0, 0);
;         }
;         __syncthreads();
; #pragma unroll
;         for (int mi = 0; mi < 4; ++mi)
; #pragma unroll
;             for (int ni = 0; ni < 4; ++ni) *(LAS f32x4*)(red + (wid * 64 + mi * 16 + fr) * 68 + ni * 16 + 4 * fq) = acc[mi][ni];
;         __syncthreads();
	v_mfma_f32_16x16x32_bf16 v[86:89], v[78:81], v[110:113], v[86:89]
	v_mfma_f32_16x16x32_bf16 v[102:105], v[78:81], v[28:31], v[102:105]
	v_mfma_f32_16x16x32_bf16 v[94:97], v[114:117], v[28:31], v[94:97]
	v_mfma_f32_16x16x32_bf16 v[146:149], v[114:117], v[130:133], v[36:39]
	v_mfma_f32_16x16x32_bf16 v[106:109], v[78:81], v[130:133], v[106:109]
	v_mfma_f32_16x16x32_bf16 v[62:65], v[98:101], v[130:133], v[62:65]
	v_mfma_f32_16x16x32_bf16 v[142:145], v[98:101], v[28:31], v[32:35]
	v_mfma_f32_16x16x32_bf16 v[36:39], v[114:117], v[134:137], v[66:69]
	v_mfma_f32_16x16x32_bf16 v[28:31], v[78:81], v[134:137], v[90:93]
	v_mfma_f32_16x16x32_bf16 v[20:23], v[98:101], v[134:137], v[20:23]
	v_mfma_f32_16x16x32_bf16 v[110:113], v[98:101], v[110:113], v[24:27]
	v_mfma_f32_16x16x32_bf16 v[24:27], v[82:85], v[118:121], v[122:125]
	v_mfma_f32_16x16x32_bf16 v[32:35], v[82:85], v[126:129], v[40:43]
	v_mfma_f32_16x16x32_bf16 v[40:43], v[82:85], v[12:15], v[70:73]
	s_waitcnt vmcnt(2)
	v_mfma_f32_16x16x32_bf16 v[70:73], v[16:19], v[118:121], v[74:77]
	s_waitcnt vmcnt(1)
	v_mfma_f32_16x16x32_bf16 v[74:77], v[8:11], v[118:121], v[86:89]
	v_mfma_f32_16x16x32_bf16 v[86:89], v[8:11], v[126:129], v[102:105]
	s_nop 2
	v_add_u32_e32 v104, s11, v49
	v_or_b32_e32 v102, s12, v50
	v_ashrrev_i32_e32 v105, 31, v104
	v_mfma_f32_16x16x32_bf16 v[66:69], v[82:85], v[0:3], v[138:141]
	v_ashrrev_i32_e32 v103, 31, v102
	v_mfma_f32_16x16x32_bf16 v[82:85], v[16:19], v[126:129], v[94:97]
	v_mfma_f32_16x16x32_bf16 v[94:97], v[16:19], v[12:15], v[146:149]
	v_mfma_f32_16x16x32_bf16 v[98:101], v[8:11], v[12:15], v[106:109]
	s_nop 2
	v_lshlrev_b64 v[108:109], 7, v[104:105]
	s_waitcnt vmcnt(0)
	v_mfma_f32_16x16x32_bf16 v[12:15], v[4:7], v[12:15], v[62:65]
	v_lshlrev_b64 v[106:107], 2, v[102:103]
	s_nop 1
	v_lshlrev_b64 v[64:65], 13, v[104:105]
	v_mfma_f32_16x16x32_bf16 v[16:19], v[16:19], v[0:3], v[36:39]
	v_lshl_add_u64 v[104:105], s[90:91], 0, v[108:109]
	v_lshl_add_u64 v[62:63], s[0:1], 0, v[106:107]
	v_lshl_add_u64 v[106:107], s[8:9], 0, v[106:107]
	v_lshl_add_u64 v[36:37], s[44:45], 0, v[64:65]
	v_mfma_f32_16x16x32_bf16 v[8:11], v[8:11], v[0:3], v[28:31]
	v_lshl_add_u64 v[130:131], v[102:103], 1, v[36:37]
	v_mfma_f32_16x16x32_bf16 v[0:3], v[4:7], v[0:3], v[20:23]
	v_mfma_f32_16x16x32_bf16 v[78:81], v[4:7], v[118:121], v[110:113]
	v_mfma_f32_16x16x32_bf16 v[90:93], v[4:7], v[126:129], v[142:145]
	ds_write_b128 v60, v[24:27]
	ds_write_b128 v60, v[32:35] offset:4352
	ds_write_b128 v60, v[40:43] offset:8704
	ds_write_b128 v60, v[66:69] offset:13056
	ds_write_b128 v60, v[70:73] offset:64
	ds_write_b128 v60, v[74:77] offset:128
	s_nop 0
	ds_write_b128 v60, v[78:81] offset:192
	ds_write_b128 v60, v[82:85] offset:4416
	ds_write_b128 v60, v[86:89] offset:4480
	ds_write_b128 v60, v[90:93] offset:4544
	ds_write_b128 v60, v[94:97] offset:8768
	ds_write_b128 v60, v[98:101] offset:8832
	ds_write_b128 v60, v[12:15] offset:8896
	ds_write_b128 v60, v[16:19] offset:13120
	ds_write_b128 v60, v[8:11] offset:13184
	ds_write_b128 v60, v[0:3] offset:13248
	s_waitcnt lgkmcnt(0)
	s_barrier
; __device__ __forceinline__ u32x4 pack8(const f32x4 a, const f32x4 b) { u32x4 w; w.x = cvt_pk_bf16(a[0], a[1]); w.y = cvt_pk_bf16(a[2], a[3]); w.z = cvt_pk_bf16(b[0], b[1]); w.w = cvt_pk_bf16(b[2], b[3]); return w; }
;     __device__ __forceinline__ void small(size_t row, int col, const f32x4 v0, const f32x4 v1) const { *(u32x4*)(Ub + row * DSSM + col) = pack8(v0, v1); }
;     __device__ __forceinline__ void piece(size_t row, int col, f32x4 v0, f32x4 v1, const f32x4 a0, const f32x4 a1, const f32x4 b0, const f32x4 b1, const f32x4 c0, const f32x4 c1,
;                                           float mean, float rstd, float& s, float& ss) const {
;     ...
;         if constexpr (MODE == 4) { v0 = (v0 - a0 * mean) * rstd + b0; v1 = (v1 - a1 * mean) * rstd + b1;
; #pragma unroll
;             for (int e = 0; e < 4; ++e) { const float x = fmaxf(v0[e], 0.f), y = fmaxf(v1[e], 0.f); v0[e] = x * x; v1[e] = y * y; } }
;         if constexpr (PROD) {
; #pragma unroll
;             for (int e = 0; e < 4; ++e) { s += v0[e] + v1[e]; ss += v0[e] * v0[e] + v1[e] * v1[e]; } }
;         if constexpr (MODE == 5) { float* o = (float*)O + row * ldo + col; *(f32x4*)o = v0; *(f32x4*)(o + 4) = v1; }
;         else *(u32x4*)((bf16_t*)O + row * ldo + col) = pack8(v0, v1);
;     __device__ __forceinline__ void small(size_t row, int col, const f32x4 v0, const f32x4 v1) const {
;         const f32x4 z = (f32x4){0.f, 0.f, 0.f, 0.f};
;         float mean = 0.f, rstd = 0.f;
;         if constexpr (CONS) { float s0, q0, s1, q1; stats_of(st_in, row, 0, s0, q0); stats_of(st_in, row, 1, s1, q1); mean = (s0 + s1) * (1.f / DM); rstd = __builtin_amdgcn_rsqf(fmaxf((q0 + q1) * (1.f / DM) - mean * mean, 0.f) + LN_EPS); }
;         float s = 0.f, ss = 0.f;
;         piece(row, col, v0, v1, CONS ? *(const f32x4*)(va + col) : z, CONS ? *(const f32x4*)(va + col + 4) : z, CONS ? *(const f32x4*)(vb + col) : z, CONS ? *(const f32x4*)(vb + col + 4) : z,
;               (MODE == 5) ? *(const f32x4*)(bias + col) : z, (MODE == 5) ? *(const f32x4*)(bias + col + 4) : z, mean, rstd, s, ss);
	global_load_dwordx4 v[0:3], v[104:105], off
	global_load_dwordx4 v[4:7], v[104:105], off offset:16
	global_load_dwordx4 v[8:11], v[104:105], off offset:32
	global_load_dwordx4 v[12:15], v[104:105], off offset:48
	global_load_dwordx4 v[16:19], v[104:105], off offset:64
	global_load_dwordx4 v[20:23], v[104:105], off offset:80
	global_load_dwordx4 v[24:27], v[104:105], off offset:96
	global_load_dwordx4 v[28:31], v[104:105], off offset:112
	global_load_dwordx4 v[32:35], v[62:63], off
	global_load_dwordx4 v[36:39], v[62:63], off offset:16
	ds_read_b128 v[40:43], v51
	ds_read_b128 v[62:65], v51 offset:16
	global_load_dwordx4 v[66:69], v[106:107], off offset:16
	global_load_dwordx4 v[70:73], v[106:107], off
	ds_read_b128 v[74:77], v51 offset:17408
	ds_read_b128 v[78:81], v51 offset:17424
	ds_read_b128 v[82:85], v51 offset:34816
	ds_read_b128 v[86:89], v51 offset:34832
	ds_read_b128 v[90:93], v51 offset:52224
	ds_read_b128 v[94:97], v51 offset:52240
	ds_read_b128 v[98:101], v52
	ds_read_b128 v[102:105], v53
	ds_read_b128 v[106:109], v54
	ds_read_b128 v[110:113], v55
	ds_read_b128 v[114:117], v56
	ds_read_b128 v[118:121], v57
	ds_read_b128 v[122:125], v58
	ds_read_b128 v[126:129], v59
	s_waitcnt lgkmcnt(14)
	v_pk_add_f32 v[40:41], v[40:41], 0 op_sel_hi:[1,0]
	v_pk_add_f32 v[42:43], v[42:43], 0 op_sel_hi:[1,0]
	v_pk_add_f32 v[64:65], v[64:65], 0 op_sel_hi:[1,0]
	v_pk_add_f32 v[62:63], v[62:63], 0 op_sel_hi:[1,0]
	s_waitcnt lgkmcnt(13)
	v_pk_add_f32 v[40:41], v[40:41], v[74:75]
	v_pk_add_f32 v[42:43], v[42:43], v[76:77]
	s_waitcnt lgkmcnt(12)
	v_pk_add_f32 v[64:65], v[64:65], v[80:81]
	v_pk_add_f32 v[62:63], v[62:63], v[78:79]
	s_waitcnt lgkmcnt(11)
	v_pk_add_f32 v[40:41], v[40:41], v[82:83]
	v_pk_add_f32 v[42:43], v[42:43], v[84:85]
	s_waitcnt lgkmcnt(10)
	v_pk_add_f32 v[64:65], v[64:65], v[88:89]
	v_pk_add_f32 v[62:63], v[62:63], v[86:87]
	s_waitcnt lgkmcnt(9)
	v_pk_add_f32 v[40:41], v[40:41], v[90:91]
	v_pk_add_f32 v[42:43], v[42:43], v[92:93]
	s_waitcnt lgkmcnt(8)
	v_pk_add_f32 v[64:65], v[64:65], v[96:97]
	v_pk_add_f32 v[62:63], v[62:63], v[94:95]
	s_waitcnt lgkmcnt(7)
	v_pk_add_f32 v[40:41], v[40:41], v[98:99]
	v_pk_add_f32 v[42:43], v[42:43], v[100:101]
	s_waitcnt lgkmcnt(6)
	v_pk_add_f32 v[64:65], v[64:65], v[104:105]
	v_pk_add_f32 v[62:63], v[62:63], v[102:103]
	s_waitcnt lgkmcnt(5)
	v_pk_add_f32 v[40:41], v[40:41], v[106:107]
	v_pk_add_f32 v[42:43], v[42:43], v[108:109]
	s_waitcnt lgkmcnt(4)
	v_pk_add_f32 v[64:65], v[64:65], v[112:113]
	v_pk_add_f32 v[62:63], v[62:63], v[110:111]
	s_waitcnt lgkmcnt(3)
	v_pk_add_f32 v[40:41], v[40:41], v[114:115]
	v_pk_add_f32 v[42:43], v[42:43], v[116:117]
	s_waitcnt lgkmcnt(2)
	v_pk_add_f32 v[64:65], v[64:65], v[120:121]
	v_pk_add_f32 v[62:63], v[62:63], v[118:119]
	s_waitcnt lgkmcnt(1)
	v_pk_add_f32 v[40:41], v[40:41], v[122:123]
	v_pk_add_f32 v[42:43], v[42:43], v[124:125]
	s_waitcnt lgkmcnt(0)
	v_pk_add_f32 v[64:65], v[64:65], v[128:129]
	v_pk_add_f32 v[62:63], v[62:63], v[126:127]
	s_waitcnt vmcnt(11)
	v_pk_add_f32 v[0:1], v[0:1], v[2:3]
	s_waitcnt vmcnt(10)
	v_pk_add_f32 v[2:3], v[4:5], v[6:7]
	s_waitcnt vmcnt(9)
	v_pk_add_f32 v[4:5], v[8:9], v[10:11]
	v_pk_add_f32 v[0:1], v[0:1], 0 op_sel_hi:[1,0]
	s_waitcnt vmcnt(7)
	v_pk_add_f32 v[8:9], v[16:17], v[18:19]
	s_waitcnt vmcnt(6)
	v_pk_add_f32 v[10:11], v[20:21], v[22:23]
	v_pk_add_f32 v[8:9], v[8:9], 0 op_sel_hi:[1,0]
	v_pk_add_f32 v[6:7], v[12:13], v[14:15]
	s_waitcnt vmcnt(5)
	v_pk_add_f32 v[12:13], v[24:25], v[26:27]
	v_pk_add_f32 v[0:1], v[0:1], v[2:3]
	v_pk_add_f32 v[2:3], v[8:9], v[10:11]
	s_waitcnt vmcnt(4)
	v_pk_add_f32 v[14:15], v[28:29], v[30:31]
	v_pk_add_f32 v[0:1], v[0:1], v[4:5]
	v_pk_add_f32 v[2:3], v[2:3], v[12:13]
	v_pk_add_f32 v[0:1], v[0:1], v[6:7]
	v_pk_add_f32 v[2:3], v[2:3], v[14:15]
	s_waitcnt vmcnt(3)
	v_xor_b32_e32 v17, 0x80000000, v35
	v_pk_add_f32 v[0:1], v[0:1], v[2:3]
	v_xor_b32_e32 v16, 0x80000000, v34
	v_pk_mul_f32 v[0:1], v[0:1], s[10:11] op_sel_hi:[1,0]
	s_waitcnt vmcnt(2)
	v_xor_b32_e32 v19, 0x80000000, v39
	v_fma_f32 v8, -v0, v0, v1
	v_max_f32_e32 v8, 0, v8
	v_add_f32_e32 v8, 0x3727c5ac, v8
	v_rsq_f32_e32 v8, v8
	v_xor_b32_e32 v18, 0x80000000, v38
	v_pk_fma_f32 v[2:3], v[32:33], v[0:1], v[40:41] op_sel_hi:[1,0,1] neg_lo:[1,0,0] neg_hi:[1,0,0]
	v_pk_fma_f32 v[4:5], v[16:17], v[0:1], v[42:43] op_sel_hi:[1,0,1]
	v_pk_fma_f32 v[6:7], v[36:37], v[0:1], v[62:63] op_sel_hi:[1,0,1] neg_lo:[1,0,0] neg_hi:[1,0,0]
	v_pk_fma_f32 v[0:1], v[18:19], v[0:1], v[64:65] op_sel_hi:[1,0,1]
	s_waitcnt vmcnt(0)
	v_pk_fma_f32 v[2:3], v[2:3], v[8:9], v[70:71] op_sel_hi:[1,0,1]
	v_pk_fma_f32 v[4:5], v[4:5], v[8:9], v[72:73] op_sel_hi:[1,0,1]
	v_pk_fma_f32 v[0:1], v[0:1], v[8:9], v[68:69] op_sel_hi:[1,0,1]
	v_pk_fma_f32 v[6:7], v[6:7], v[8:9], v[66:67] op_sel_hi:[1,0,1]
	v_max_f32_e32 v2, 0, v2
	v_max_f32_e32 v3, 0, v3
	v_max_f32_e32 v6, 0, v6
	v_max_f32_e32 v7, 0, v7
	v_max_f32_e32 v4, 0, v4
	v_max_f32_e32 v0, 0, v0
	v_max_f32_e32 v5, 0, v5
	v_max_f32_e32 v1, 0, v1
	v_mul_f32_e32 v2, v2, v2
	v_mul_f32_e32 v3, v3, v3
	v_mul_f32_e32 v6, v6, v6
	v_mul_f32_e32 v7, v7, v7
	v_mul_f32_e32 v4, v4, v4
	v_mul_f32_e32 v8, v0, v0
	v_mul_f32_e32 v5, v5, v5
	v_mul_f32_e32 v9, v1, v1
	v_cvt_pk_bf16_f32 v0, v2, v3
	v_cvt_pk_bf16_f32 v1, v4, v5
	v_cvt_pk_bf16_f32 v2, v6, v7
	v_cvt_pk_bf16_f32 v3, v8, v9
	global_store_dwordx4 v[130:131], v[0:3], off sc0 sc1
	s_cbranch_scc1 .LBB0_1387
